# mlstm_pre key column sums without LDS atomics: DPP row reduction, then 16 lanes per wave write per-(wave,row) partials to conflict-free LDS slots; the final read sums the 16 partials
# speedup vs baseline: 1.0039x; 1.0039x over previous
; DI void conv32(const bf16_t* __restrict__ Pcol, int tok, int spos, const float* wl, int wstride, float* acc) {
; #pragma unroll
;   for (int hq = 0; hq < 2; ++hq) {
;     __builtin_amdgcn_sched_barrier(0);
;     uint4 v[4][2];
; #pragma unroll
;     for (int j = 0; j < 4; ++j) {
;       const bool ok = (spos - 3 + j >= 0);
;       const uint4* src = (const uint4*)(Pcol + (size_t)(tok - 3 + (ok ? j : 3)) * 4096) + 2 * hq;
; #pragma unroll
;       for (int q = 0; q < 2; ++q) {
;         v[j][q] = src[q];
;         if (!ok) v[j][q] = make_uint4(0u, 0u, 0u, 0u);
;       }
;     }
; #pragma unroll
;     for (int i = 0; i < 16; ++i) acc[16 * hq + i] = 0.f;
; #pragma unroll
;     for (int j = 0; j < 4; ++j) {
;       const float4* w4 = (const float4*)(wl + j * wstride + 16 * hq);
; #pragma unroll
;       for (int q = 0; q < 2; ++q) {
;         float f[8];
;         unpack8(v[j][q], f);
;         float4 wa = w4[2 * q], wb = w4[2 * q + 1];
;         float* a = acc + 16 * hq + 8 * q;
;         a[0] += wa.x * f[0]; a[1] += wa.y * f[1]; a[2] += wa.z * f[2]; a[3] += wa.w * f[3];
;         a[4] += wb.x * f[4]; a[5] += wb.y * f[5]; a[6] += wb.z * f[6]; a[7] += wb.w * f[7];
;       }
;     }
; DI void mlstm_pre(const Params& p, int ch, char* smem) {
;     ...
;   const int t = tid >> 2, part = tid & 3;
;   const float wgt = __expf(b_last - s_bc[t] + s_li[t] - m_new);
;   {
;     float a[32];
;     conv32(P + 2048 + h * 128 + part * 32, tok0 + t, c * 64 + t, s_w + part * 32, 256, a);
.LBB0_404:
	s_or_b64 exec, exec, s[10:11]
	s_mul_i32 s9, s44, 0xe000
	s_mul_hi_i32 s8, s44, 0xe000
	s_add_u32 s60, s84, s9
	s_waitcnt vmcnt(63) expcnt(7) lgkmcnt(15)
	s_barrier
	ds_read2st64_b32 v[2:3], v2 offset0:136 offset1:138
	s_addc_u32 s61, s85, s8
	s_add_u32 s66, s60, 0x4000
	s_addc_u32 s67, s61, 0
	s_add_u32 s64, s60, 0x8000
	s_addc_u32 s65, s61, 0
	s_waitcnt lgkmcnt(0)
	v_sub_f32_e32 v0, v0, v3
	s_lshl_b32 s34, s34, 8
	v_add_f32_e32 v0, v0, v2
	s_add_u32 s8, s3, s34
	v_sub_f32_e32 v0, v0, v1
	s_addc_u32 s9, s4, 0
	v_add_u32_e32 v8, s70, v79
	v_mul_f32_e32 v0, 0x3fb8aa3b, v0
	v_lshl_add_u64 v[16:17], s[8:9], 0, v[28:29]
	v_add_u32_e32 v9, s90, v79
	v_add_u32_e32 v18, -3, v8
	v_exp_f32_e32 v83, v0
	v_lshlrev_b32_e32 v84, 7, v81
	v_cmp_lt_i32_e64 s[10:11], 2, v9
	v_cmp_lt_i32_e64 s[12:13], 1, v9
	v_cmp_lt_i32_e64 s[14:15], 0, v9
	v_cndmask_b32_e64 v0, v8, v18, s[10:11]
	v_ashrrev_i32_e32 v1, 31, v0
	v_lshlrev_b64 v[10:11], 13, v[0:1]
	v_lshl_add_u64 v[22:23], v[16:17], 0, v[10:11]
	global_load_dwordx4 v[0:3], v[22:23], off offset:16
	global_load_dwordx4 v[4:7], v[22:23], off
	v_cmp_lt_i32_e64 s[8:9], -1, v9
	v_ashrrev_i32_e32 v9, 31, v8
	v_lshlrev_b64 v[8:9], 13, v[8:9]
	v_lshl_add_u64 v[36:37], v[16:17], 0, v[8:9]
	s_waitcnt vmcnt(1)
	v_cndmask_b32_e64 v35, 0, v0, s[10:11]
	v_cndmask_b32_e64 v0, 3, 1, s[12:13]
	v_add_u32_e32 v0, v0, v18
	v_cndmask_b32_e64 v34, 0, v1, s[10:11]
	v_ashrrev_i32_e32 v1, 31, v0
	s_waitcnt vmcnt(0)
	v_cndmask_b32_e64 v24, 0, v7, s[10:11]
	v_cndmask_b32_e64 v25, 0, v6, s[10:11]
	v_lshlrev_b64 v[6:7], 13, v[0:1]
	v_lshl_add_u64 v[20:21], v[16:17], 0, v[6:7]
	v_cndmask_b32_e64 v32, 0, v3, s[10:11]
	v_cndmask_b32_e64 v33, 0, v2, s[10:11]
	global_load_dwordx4 v[0:3], v[20:21], off offset:16
	global_load_dwordx4 v[12:15], v[20:21], off
	v_cndmask_b32_e64 v26, 0, v5, s[10:11]
	v_cndmask_b32_e64 v27, 0, v4, s[10:11]
	v_lshlrev_b32_e32 v58, 16, v26
	v_and_b32_e32 v59, 0xffff0000, v26
	v_lshlrev_b32_e32 v64, 16, v35
	v_and_b32_e32 v65, 0xffff0000, v35
	v_lshlrev_b32_e32 v86, 16, v34
	v_and_b32_e32 v87, 0xffff0000, v34
	v_lshlrev_b32_e32 v88, 16, v33
	v_and_b32_e32 v89, 0xffff0000, v33
	v_lshlrev_b32_e32 v60, 16, v25
	v_and_b32_e32 v61, 0xffff0000, v25
	v_lshlrev_b32_e32 v62, 16, v24
	v_and_b32_e32 v63, 0xffff0000, v24
	s_waitcnt vmcnt(1)
	v_cndmask_b32_e64 v45, 0, v0, s[12:13]
	v_cndmask_b32_e64 v0, 3, 2, s[14:15]
	v_add_u32_e32 v0, v0, v18
	v_cndmask_b32_e64 v44, 0, v1, s[12:13]
	v_ashrrev_i32_e32 v1, 31, v0
	v_lshlrev_b64 v[4:5], 13, v[0:1]
	v_lshl_add_u64 v[18:19], v[16:17], 0, v[4:5]
	s_waitcnt vmcnt(0)
	v_cndmask_b32_e64 v38, 0, v15, s[12:13]
	v_cndmask_b32_e64 v39, 0, v14, s[12:13]
	v_cndmask_b32_e64 v40, 0, v13, s[12:13]
	v_cndmask_b32_e64 v41, 0, v12, s[12:13]
	v_cndmask_b32_e64 v42, 0, v3, s[12:13]
	v_cndmask_b32_e64 v43, 0, v2, s[12:13]
	global_load_dwordx4 v[0:3], v[18:19], off offset:16
	global_load_dwordx4 v[12:15], v[18:19], off
	v_lshlrev_b32_e32 v16, 16, v27
	v_and_b32_e32 v17, 0xffff0000, v27
	v_lshlrev_b32_e32 v26, 16, v41
	v_and_b32_e32 v27, 0xffff0000, v41
	v_lshlrev_b32_e32 v90, 16, v40
	v_and_b32_e32 v91, 0xffff0000, v40
	v_lshlrev_b32_e32 v92, 16, v39
	v_and_b32_e32 v93, 0xffff0000, v39
	v_lshlrev_b32_e32 v94, 16, v38
	v_and_b32_e32 v95, 0xffff0000, v38
	v_lshlrev_b32_e32 v96, 16, v45
	v_and_b32_e32 v97, 0xffff0000, v45
	v_lshlrev_b32_e32 v98, 16, v44
	v_and_b32_e32 v99, 0xffff0000, v44
	v_lshlrev_b32_e32 v100, 16, v43
	v_and_b32_e32 v101, 0xffff0000, v43
	s_waitcnt vmcnt(1)
	v_cndmask_b32_e64 v50, 0, v3, s[14:15]
	s_waitcnt vmcnt(0)
	v_cndmask_b32_e64 v46, 0, v15, s[14:15]
	v_cndmask_b32_e64 v47, 0, v14, s[14:15]
	v_cndmask_b32_e64 v48, 0, v13, s[14:15]
	v_cndmask_b32_e64 v49, 0, v12, s[14:15]
	v_cndmask_b32_e64 v51, 0, v2, s[14:15]
	v_cndmask_b32_e64 v52, 0, v1, s[14:15]
	v_cndmask_b32_e64 v53, 0, v0, s[14:15]
	global_load_dwordx4 v[0:3], v[36:37], off offset:16
	global_load_dwordx4 v[12:15], v[36:37], off
	v_lshlrev_b32_e32 v54, 16, v49
	v_and_b32_e32 v55, 0xffff0000, v49
	v_lshlrev_b32_e32 v102, 16, v48
	v_and_b32_e32 v103, 0xffff0000, v48
	v_lshlrev_b32_e32 v104, 16, v47
	v_and_b32_e32 v105, 0xffff0000, v47
	v_lshlrev_b32_e32 v106, 16, v46
	v_and_b32_e32 v107, 0xffff0000, v46
	v_lshlrev_b32_e32 v108, 16, v53
	v_and_b32_e32 v109, 0xffff0000, v53
	v_lshlrev_b32_e32 v110, 16, v52
	v_and_b32_e32 v111, 0xffff0000, v52
	v_lshlrev_b32_e32 v112, 16, v51
	v_and_b32_e32 v113, 0xffff0000, v51
	v_lshlrev_b32_e32 v24, 16, v50
	v_and_b32_e32 v25, 0xffff0000, v50
	s_waitcnt vmcnt(1)
	v_cndmask_b32_e64 v122, 0, v3, s[8:9]
	s_waitcnt vmcnt(0)
	v_cndmask_b32_e64 v56, 0, v15, s[8:9]
	v_cndmask_b32_e64 v57, 0, v14, s[8:9]
	v_cndmask_b32_e64 v85, 0, v13, s[8:9]
	v_cndmask_b32_e64 v115, 0, v12, s[8:9]
	v_cndmask_b32_e64 v123, 0, v2, s[8:9]
	v_cndmask_b32_e64 v124, 0, v1, s[8:9]
	v_cndmask_b32_e64 v125, 0, v0, s[8:9]
	v_lshlrev_b32_e32 v12, 16, v32
	v_and_b32_e32 v13, 0xffff0000, v32
	v_lshlrev_b32_e32 v14, 16, v42
	v_and_b32_e32 v15, 0xffff0000, v42
	ds_read_b128 v[32:35], v84 offset:40960
	ds_read_b128 v[38:41], v84 offset:40976
	ds_read_b128 v[42:45], v84 offset:40992
	ds_read_b128 v[0:3], v84 offset:41008
	ds_read_b128 v[46:49], v84 offset:41984
	ds_read_b128 v[50:53], v84 offset:43008
	s_waitcnt lgkmcnt(5)
	v_pk_fma_f32 v[16:17], v[32:33], v[16:17], 0 op_sel_hi:[1,1,0]
	v_lshlrev_b32_e32 v118, 16, v57
	v_and_b32_e32 v119, 0xffff0000, v57
	s_waitcnt lgkmcnt(1)
	v_pk_fma_f32 v[16:17], v[46:47], v[26:27], v[16:17]
	v_lshlrev_b32_e32 v120, 16, v56
	v_and_b32_e32 v121, 0xffff0000, v56
	s_waitcnt lgkmcnt(0)
; DI float sigmoidf_(float x) { return __builtin_amdgcn_rcpf(1.f + __expf(-x)); }
; DI void conv32(const bf16_t* __restrict__ Pcol, int tok, int spos, const float* wl, int wstride, float* acc) {
;     ...
; #pragma unroll
;     for (int j = 0; j < 4; ++j) {
;       const bool ok = (spos - 3 + j >= 0);
;       const uint4* src = (const uint4*)(Pcol + (size_t)(tok - 3 + (ok ? j : 3)) * 4096) + 2 * hq;
; #pragma unroll
;       for (int q = 0; q < 2; ++q) {
;         v[j][q] = src[q];
;         if (!ok) v[j][q] = make_uint4(0u, 0u, 0u, 0u);
;       }
;     }
; #pragma unroll
;     for (int i = 0; i < 16; ++i) acc[16 * hq + i] = 0.f;
; #pragma unroll
;     for (int j = 0; j < 4; ++j) {
;       const float4* w4 = (const float4*)(wl + j * wstride + 16 * hq);
; #pragma unroll
;       for (int q = 0; q < 2; ++q) {
;         float f[8];
;         unpack8(v[j][q], f);
;         float4 wa = w4[2 * q], wb = w4[2 * q + 1];
;         float* a = acc + 16 * hq + 8 * q;
;         a[0] += wa.x * f[0]; a[1] += wa.y * f[1]; a[2] += wa.z * f[2]; a[3] += wa.w * f[3];
;         a[4] += wb.x * f[4]; a[5] += wb.y * f[5]; a[6] += wb.z * f[6]; a[7] += wb.w * f[7];
;       }
;     }
; #pragma unroll
;     for (int i = 0; i < 16; ++i) acc[16 * hq + i] = acc[16 * hq + i] * sigmoidf_(acc[16 * hq + i]);
;   }
	v_pk_fma_f32 v[16:17], v[50:51], v[54:55], v[16:17]
	ds_read_b128 v[54:57], v84 offset:44032
	v_lshlrev_b32_e32 v114, 16, v115
	v_and_b32_e32 v115, 0xffff0000, v115
	v_pk_fma_f32 v[38:39], v[38:39], v[60:61], 0 op_sel_hi:[1,1,0]
	v_lshlrev_b32_e32 v116, 16, v85
	s_waitcnt lgkmcnt(0)
	v_pk_fma_f32 v[26:27], v[54:55], v[114:115], v[16:17]
	v_pk_fma_f32 v[16:17], v[34:35], v[58:59], 0 op_sel_hi:[1,1,0]
	ds_read_b128 v[32:35], v84 offset:42000
	v_pk_fma_f32 v[16:17], v[48:49], v[90:91], v[16:17]
	ds_read_b128 v[46:49], v84 offset:43024
	v_pk_fma_f32 v[16:17], v[52:53], v[102:103], v[16:17]
	ds_read_b128 v[50:53], v84 offset:44048
	s_waitcnt lgkmcnt(2)
	v_pk_fma_f32 v[32:33], v[32:33], v[92:93], v[38:39]
	v_pk_fma_f32 v[38:39], v[42:43], v[64:65], 0 op_sel_hi:[1,1,0]
	s_waitcnt lgkmcnt(1)
	v_pk_fma_f32 v[32:33], v[46:47], v[104:105], v[32:33]
	v_lshlrev_b32_e32 v54, 16, v125
	s_waitcnt lgkmcnt(0)
	v_pk_fma_f32 v[50:51], v[50:51], v[118:119], v[32:33]
	v_pk_fma_f32 v[32:33], v[40:41], v[62:63], 0 op_sel_hi:[1,1,0]
	v_and_b32_e32 v55, 0xffff0000, v125
	v_pk_fma_f32 v[32:33], v[34:35], v[94:95], v[32:33]
	v_and_b32_e32 v117, 0xffff0000, v85
	v_pk_fma_f32 v[32:33], v[48:49], v[106:107], v[32:33]
	ds_read_b128 v[46:49], v84 offset:44064
	v_pk_fma_f32 v[52:53], v[52:53], v[120:121], v[32:33]
	ds_read_b128 v[32:35], v84 offset:42016
	v_pk_fma_f32 v[16:17], v[56:57], v[116:117], v[16:17]
	v_lshlrev_b32_e32 v56, 16, v124
	v_and_b32_e32 v57, 0xffff0000, v124
	v_pk_fma_f32 v[0:1], v[0:1], v[88:89], 0 op_sel_hi:[1,1,0]
	s_waitcnt lgkmcnt(0)
	v_pk_fma_f32 v[32:33], v[32:33], v[96:97], v[38:39]
	ds_read_b128 v[38:41], v84 offset:43040
	v_lshlrev_b32_e32 v58, 16, v123
	v_and_b32_e32 v59, 0xffff0000, v123
	v_pk_fma_f32 v[2:3], v[2:3], v[12:13], 0 op_sel_hi:[1,1,0]
	v_mul_f32_e32 v12, 0xbfb8aa3b, v26
	s_waitcnt lgkmcnt(0)
	v_pk_fma_f32 v[32:33], v[38:39], v[108:109], v[32:33]
	v_mul_f32_e32 v13, 0xbfb8aa3b, v27
	v_pk_fma_f32 v[54:55], v[46:47], v[54:55], v[32:33]
	v_pk_fma_f32 v[32:33], v[44:45], v[86:87], 0 op_sel_hi:[1,1,0]
	ds_read_b128 v[42:45], v84 offset:43056
	v_pk_fma_f32 v[32:33], v[34:35], v[98:99], v[32:33]
	v_exp_f32_e32 v12, v12
	v_pk_fma_f32 v[32:33], v[40:41], v[110:111], v[32:33]
	ds_read_b128 v[38:41], v84 offset:42032
	v_pk_fma_f32 v[32:33], v[48:49], v[56:57], v[32:33]
	ds_read_b128 v[46:49], v84 offset:44080
	v_mul_f32_e32 v34, 0xbfb8aa3b, v32
	v_mul_f32_e32 v35, 0xbfb8aa3b, v33
	v_exp_f32_e32 v34, v34
	v_exp_f32_e32 v35, v35
	s_waitcnt lgkmcnt(1)
	v_pk_fma_f32 v[0:1], v[38:39], v[100:101], v[0:1]
	v_pk_fma_f32 v[2:3], v[40:41], v[14:15], v[2:3]
	v_add_f32_e32 v34, 1.0, v34
	v_add_f32_e32 v35, 1.0, v35
	v_rcp_f32_e32 v34, v34
	v_rcp_f32_e32 v35, v35
	v_pk_fma_f32 v[0:1], v[42:43], v[112:113], v[0:1]
	v_mul_f32_e32 v14, 0xbfb8aa3b, v16
	s_waitcnt lgkmcnt(0)
	v_pk_fma_f32 v[0:1], v[46:47], v[58:59], v[0:1]
	v_mul_f32_e32 v15, 0xbfb8aa3b, v17
	v_exp_f32_e32 v14, v14
	v_exp_f32_e32 v15, v15
	v_pk_mul_f32 v[32:33], v[32:33], v[34:35]
	v_mul_f32_e32 v34, 0xbfb8aa3b, v0
	v_mul_f32_e32 v35, 0xbfb8aa3b, v1
	v_exp_f32_e32 v13, v13
	v_exp_f32_e32 v34, v34
	v_exp_f32_e32 v35, v35
	v_add_f32_e32 v14, 1.0, v14
	v_add_f32_e32 v15, 1.0, v15
	v_add_f32_e32 v12, 1.0, v12
	v_add_f32_e32 v13, 1.0, v13
	v_rcp_f32_e32 v14, v14
	v_rcp_f32_e32 v15, v15
	v_add_f32_e32 v34, 1.0, v34
	v_add_f32_e32 v35, 1.0, v35
	v_rcp_f32_e32 v12, v12
	v_rcp_f32_e32 v13, v13
	v_rcp_f32_e32 v34, v34
	v_rcp_f32_e32 v35, v35
	v_lshlrev_b32_e32 v60, 16, v122
	v_and_b32_e32 v61, 0xffff0000, v122
	v_pk_fma_f32 v[2:3], v[44:45], v[24:25], v[2:3]
	v_pk_mul_f32 v[14:15], v[16:17], v[14:15]
	v_pk_fma_f32 v[2:3], v[48:49], v[60:61], v[2:3]
	v_mul_f32_e32 v16, 0xbfb8aa3b, v50
	v_mul_f32_e32 v17, 0xbfb8aa3b, v51
	v_mul_f32_e32 v24, 0xbfb8aa3b, v52
	v_mul_f32_e32 v25, 0xbfb8aa3b, v53
	v_pk_mul_f32 v[12:13], v[26:27], v[12:13]
	v_exp_f32_e32 v16, v16
	v_exp_f32_e32 v17, v17
	v_exp_f32_e32 v24, v24
	v_exp_f32_e32 v25, v25
	v_mul_f32_e32 v26, 0xbfb8aa3b, v54
	v_mul_f32_e32 v27, 0xbfb8aa3b, v55
	v_pk_mul_f32 v[34:35], v[0:1], v[34:35]
	v_mul_f32_e32 v0, 0xbfb8aa3b, v2
	v_mul_f32_e32 v1, 0xbfb8aa3b, v3
	v_exp_f32_e32 v26, v26
	v_exp_f32_e32 v27, v27
	v_exp_f32_e32 v0, v0
	v_exp_f32_e32 v1, v1
	v_add_f32_e32 v16, 1.0, v16
	v_add_f32_e32 v17, 1.0, v17
	v_add_f32_e32 v24, 1.0, v24
	v_add_f32_e32 v25, 1.0, v25
	v_rcp_f32_e32 v16, v16
	v_rcp_f32_e32 v17, v17
	v_rcp_f32_e32 v24, v24
	v_rcp_f32_e32 v25, v25
	v_add_f32_e32 v26, 1.0, v26
	v_add_f32_e32 v27, 1.0, v27
	v_add_f32_e32 v0, 1.0, v0
	v_add_f32_e32 v1, 1.0, v1
	v_rcp_f32_e32 v26, v26
	v_rcp_f32_e32 v27, v27
	v_rcp_f32_e32 v0, v0
	v_rcp_f32_e32 v1, v1
	v_pk_mul_f32 v[16:17], v[50:51], v[16:17]
	v_pk_mul_f32 v[24:25], v[52:53], v[24:25]
	v_pk_mul_f32 v[26:27], v[54:55], v[26:27]
	v_pk_mul_f32 v[38:39], v[2:3], v[0:1]
	global_load_dwordx4 v[0:3], v[22:23], off offset:32
	global_load_dwordx4 v[40:43], v[22:23], off offset:48
	global_load_dwordx4 v[44:47], v[20:21], off offset:32
	s_nop 0
	global_load_dwordx4 v[20:23], v[20:21], off offset:48
	s_nop 0
	global_load_dwordx4 v[48:51], v[18:19], off offset:32
	global_load_dwordx4 v[52:55], v[18:19], off offset:48
	global_load_dwordx4 v[56:59], v[36:37], off offset:32
	global_load_dwordx4 v[60:63], v[36:37], off offset:48
	s_waitcnt vmcnt(7)
	v_cndmask_b32_e64 v3, 0, v3, s[10:11]
	v_cndmask_b32_e64 v2, 0, v2, s[10:11]
	v_cndmask_b32_e64 v1, 0, v1, s[10:11]
	v_cndmask_b32_e64 v0, 0, v0, s[10:11]
	s_waitcnt vmcnt(6)
	v_cndmask_b32_e64 v19, 0, v43, s[10:11]
	v_cndmask_b32_e64 v18, 0, v42, s[10:11]
	v_cndmask_b32_e64 v36, 0, v41, s[10:11]
	v_cndmask_b32_e64 v37, 0, v40, s[10:11]
	s_waitcnt vmcnt(5)
; DI float sigmoidf_(float x) { return __builtin_amdgcn_rcpf(1.f + __expf(-x)); }
; DI void conv32(const bf16_t* __restrict__ Pcol, int tok, int spos, const float* wl, int wstride, float* acc) {
;     ...
; #pragma unroll
;     for (int j = 0; j < 4; ++j) {
;       const bool ok = (spos - 3 + j >= 0);
;       const uint4* src = (const uint4*)(Pcol + (size_t)(tok - 3 + (ok ? j : 3)) * 4096) + 2 * hq;
; #pragma unroll
;       for (int q = 0; q < 2; ++q) {
;         v[j][q] = src[q];
;         if (!ok) v[j][q] = make_uint4(0u, 0u, 0u, 0u);
;       }
;     }
; #pragma unroll
;     for (int i = 0; i < 16; ++i) acc[16 * hq + i] = 0.f;
; #pragma unroll
;     for (int j = 0; j < 4; ++j) {
;       const float4* w4 = (const float4*)(wl + j * wstride + 16 * hq);
; #pragma unroll
;       for (int q = 0; q < 2; ++q) {
;         float f[8];
;         unpack8(v[j][q], f);
;         float4 wa = w4[2 * q], wb = w4[2 * q + 1];
;         float* a = acc + 16 * hq + 8 * q;
;         a[0] += wa.x * f[0]; a[1] += wa.y * f[1]; a[2] += wa.z * f[2]; a[3] += wa.w * f[3];
;         a[4] += wb.x * f[4]; a[5] += wb.y * f[5]; a[6] += wb.z * f[6]; a[7] += wb.w * f[7];
;       }
;     }
; #pragma unroll
;     for (int i = 0; i < 16; ++i) acc[16 * hq + i] = acc[16 * hq + i] * sigmoidf_(acc[16 * hq + i]);
;   }
	v_cndmask_b32_e64 v40, 0, v47, s[12:13]
	v_cndmask_b32_e64 v41, 0, v46, s[12:13]
	v_cndmask_b32_e64 v42, 0, v45, s[12:13]
	v_cndmask_b32_e64 v43, 0, v44, s[12:13]
	s_waitcnt vmcnt(4)
	v_cndmask_b32_e64 v86, 0, v22, s[12:13]
	s_waitcnt vmcnt(3)
	v_cndmask_b32_e64 v87, 0, v51, s[14:15]
	v_cndmask_b32_e64 v88, 0, v50, s[14:15]
	v_cndmask_b32_e64 v89, 0, v49, s[14:15]
	v_cndmask_b32_e64 v90, 0, v48, s[14:15]
	s_waitcnt vmcnt(2)
	v_cndmask_b32_e64 v91, 0, v55, s[14:15]
	v_cndmask_b32_e64 v92, 0, v54, s[14:15]
	s_waitcnt vmcnt(1)
	v_cndmask_b32_e64 v93, 0, v58, s[8:9]
	v_cndmask_b32_e64 v94, 0, v57, s[8:9]
	v_cndmask_b32_e64 v95, 0, v56, s[8:9]
	v_cndmask_b32_e64 v85, 0, v23, s[12:13]
	v_cndmask_b32_e64 v121, 0, v59, s[8:9]
	s_waitcnt vmcnt(0)
	v_cndmask_b32_e64 v64, 0, v63, s[8:9]
	v_cndmask_b32_e64 v65, 0, v62, s[8:9]
	v_cndmask_b32_e64 v122, 0, v61, s[8:9]
	v_cndmask_b32_e64 v123, 0, v60, s[8:9]
	v_lshlrev_b32_e32 v22, 16, v0
	v_and_b32_e32 v23, 0xffff0000, v0
	v_lshlrev_b32_e32 v102, 16, v1
	v_and_b32_e32 v103, 0xffff0000, v1
	v_lshlrev_b32_e32 v106, 16, v2
	v_and_b32_e32 v107, 0xffff0000, v2
	v_lshlrev_b32_e32 v58, 16, v3
	v_and_b32_e32 v59, 0xffff0000, v3
	v_lshlrev_b32_e32 v50, 16, v37
	v_and_b32_e32 v51, 0xffff0000, v37
	v_lshlrev_b32_e32 v46, 16, v36
	v_and_b32_e32 v47, 0xffff0000, v36
	v_lshlrev_b32_e32 v98, 16, v43
	v_and_b32_e32 v99, 0xffff0000, v43
	v_lshlrev_b32_e32 v104, 16, v42
	v_and_b32_e32 v105, 0xffff0000, v42
	v_lshlrev_b32_e32 v108, 16, v41
	v_and_b32_e32 v109, 0xffff0000, v41
	v_lshlrev_b32_e32 v60, 16, v40
	v_and_b32_e32 v61, 0xffff0000, v40
	v_lshlrev_b32_e32 v40, 16, v86
	v_and_b32_e32 v41, 0xffff0000, v86
	v_lshlrev_b32_e32 v100, 16, v90
	v_and_b32_e32 v101, 0xffff0000, v90
	v_lshlrev_b32_e32 v110, 16, v89
	v_and_b32_e32 v111, 0xffff0000, v89
	v_lshlrev_b32_e32 v112, 16, v88
	v_and_b32_e32 v113, 0xffff0000, v88
	v_lshlrev_b32_e32 v62, 16, v87
	v_and_b32_e32 v63, 0xffff0000, v87
	v_lshlrev_b32_e32 v42, 16, v92
	v_and_b32_e32 v43, 0xffff0000, v92
	v_lshlrev_b32_e32 v36, 16, v91
	v_and_b32_e32 v37, 0xffff0000, v91
	v_lshlrev_b32_e32 v114, 16, v95
	v_and_b32_e32 v115, 0xffff0000, v95
	v_lshlrev_b32_e32 v116, 16, v94
	v_and_b32_e32 v117, 0xffff0000, v94
	v_lshlrev_b32_e32 v118, 16, v93
	v_and_b32_e32 v119, 0xffff0000, v93
	ds_read_b128 v[0:3], v84 offset:41024
	ds_read_b128 v[86:89], v84 offset:42048
	ds_read_b128 v[90:93], v84 offset:43072
	ds_read_b128 v[94:97], v84 offset:44096
	v_cndmask_b32_e64 v21, 0, v21, s[12:13]
	s_waitcnt lgkmcnt(3)
	v_pk_fma_f32 v[0:1], v[0:1], v[22:23], 0 op_sel_hi:[1,1,0]
	v_cndmask_b32_e64 v20, 0, v20, s[12:13]
	s_waitcnt lgkmcnt(2)
	v_pk_fma_f32 v[0:1], v[86:87], v[98:99], v[0:1]
	v_cndmask_b32_e64 v55, 0, v53, s[14:15]
	s_waitcnt lgkmcnt(1)
	v_pk_fma_f32 v[0:1], v[90:91], v[100:101], v[0:1]
	ds_read_b128 v[98:101], v84 offset:41040
	s_waitcnt lgkmcnt(1)
	v_pk_fma_f32 v[22:23], v[94:95], v[114:115], v[0:1]
	v_cndmask_b32_e64 v54, 0, v52, s[14:15]
	v_mul_f32_e32 v0, 0xbfb8aa3b, v22
	v_exp_f32_e32 v0, v0
	v_mul_f32_e32 v1, 0xbfb8aa3b, v23
	v_exp_f32_e32 v1, v1
	v_lshlrev_b32_e32 v52, 16, v20
	v_add_f32_e32 v0, 1.0, v0
	v_rcp_f32_e32 v90, v0
	v_add_f32_e32 v0, 1.0, v1
	v_rcp_f32_e32 v91, v0
	v_pk_fma_f32 v[0:1], v[2:3], v[102:103], 0 op_sel_hi:[1,1,0]
	v_and_b32_e32 v53, 0xffff0000, v20
	v_pk_fma_f32 v[0:1], v[88:89], v[104:105], v[0:1]
	v_lshlrev_b32_e32 v48, 16, v21
	v_pk_fma_f32 v[0:1], v[92:93], v[110:111], v[0:1]
	v_and_b32_e32 v49, 0xffff0000, v21
	v_pk_fma_f32 v[110:111], v[96:97], v[116:117], v[0:1]
	v_lshlrev_b32_e32 v20, 16, v85
	v_mul_f32_e32 v0, 0xbfb8aa3b, v110
	v_and_b32_e32 v21, 0xffff0000, v85
	v_exp_f32_e32 v85, v0
	ds_read_b128 v[86:89], v84 offset:41056
	ds_read_b128 v[0:3], v84 offset:41072
	v_pk_mul_f32 v[22:23], v[22:23], v[90:91]
	ds_read_b128 v[90:93], v84 offset:42064
	ds_read_b128 v[94:97], v84 offset:43088
	ds_read_b128 v[102:105], v84 offset:44112
	s_waitcnt lgkmcnt(5)
	v_pk_fma_f32 v[98:99], v[98:99], v[106:107], 0 op_sel_hi:[1,1,0]
	v_pk_fma_f32 v[58:59], v[100:101], v[58:59], 0 op_sel_hi:[1,1,0]
	s_waitcnt lgkmcnt(2)
	v_pk_fma_f32 v[90:91], v[90:91], v[108:109], v[98:99]
	v_add_f32_e32 v85, 1.0, v85
	s_waitcnt lgkmcnt(1)
	v_pk_fma_f32 v[90:91], v[94:95], v[112:113], v[90:91]
	v_pk_fma_f32 v[58:59], v[92:93], v[60:61], v[58:59]
	v_lshlrev_b32_e32 v120, 16, v121
	v_and_b32_e32 v121, 0xffff0000, v121
	v_rcp_f32_e32 v114, v85
	v_mul_f32_e32 v85, 0xbfb8aa3b, v111
	s_waitcnt lgkmcnt(0)
	v_pk_fma_f32 v[98:99], v[102:103], v[118:119], v[90:91]
	v_pk_fma_f32 v[58:59], v[96:97], v[62:63], v[58:59]
	v_exp_f32_e32 v85, v85
	v_mul_f32_e32 v90, 0xbfb8aa3b, v98
	v_pk_fma_f32 v[62:63], v[104:105], v[120:121], v[58:59]
	v_exp_f32_e32 v90, v90
	v_mul_f32_e32 v91, 0xbfb8aa3b, v99
	v_mul_f32_e32 v58, 0xbfb8aa3b, v62
	v_exp_f32_e32 v91, v91
	v_exp_f32_e32 v58, v58
	v_mul_f32_e32 v59, 0xbfb8aa3b, v63
	v_exp_f32_e32 v59, v59
	v_add_f32_e32 v85, 1.0, v85
	v_rcp_f32_e32 v115, v85
	v_add_f32_e32 v85, 1.0, v90
	v_rcp_f32_e32 v102, v85
	v_add_f32_e32 v85, 1.0, v91
	v_add_f32_e32 v58, 1.0, v58
	v_rcp_f32_e32 v103, v85
	v_rcp_f32_e32 v100, v58
	v_add_f32_e32 v85, 1.0, v59
	ds_read_b128 v[58:61], v84 offset:42080
	ds_read_b128 v[90:93], v84 offset:43104
	ds_read_b128 v[94:97], v84 offset:44128
	v_rcp_f32_e32 v101, v85
	v_pk_fma_f32 v[50:51], v[86:87], v[50:51], 0 op_sel_hi:[1,1,0]
	v_lshlrev_b32_e32 v56, 16, v54
	v_and_b32_e32 v57, 0xffff0000, v54
	s_waitcnt lgkmcnt(2)
	v_pk_fma_f32 v[50:51], v[58:59], v[52:53], v[50:51]
	v_pk_fma_f32 v[46:47], v[88:89], v[46:47], 0 op_sel_hi:[1,1,0]
	v_lshlrev_b32_e32 v54, 16, v55
	v_and_b32_e32 v55, 0xffff0000, v55
	s_waitcnt lgkmcnt(1)
; DI float sigmoidf_(float x) { return __builtin_amdgcn_rcpf(1.f + __expf(-x)); }
; DI int fragoff(int row, int k, int KS) { return (((row >> 4) * KS + (k >> 5)) << 9) + (((((k >> 3) & 3) << 4) + (row & 15)) << 3) + (k & 7); }
; DI void conv32(const bf16_t* __restrict__ Pcol, int tok, int spos, const float* wl, int wstride, float* acc) {
;     ...
; #pragma unroll
;     for (int j = 0; j < 4; ++j) {
;       const bool ok = (spos - 3 + j >= 0);
;       const uint4* src = (const uint4*)(Pcol + (size_t)(tok - 3 + (ok ? j : 3)) * 4096) + 2 * hq;
; #pragma unroll
;       for (int q = 0; q < 2; ++q) {
;         v[j][q] = src[q];
;         if (!ok) v[j][q] = make_uint4(0u, 0u, 0u, 0u);
;       }
;     }
; #pragma unroll
;     for (int i = 0; i < 16; ++i) acc[16 * hq + i] = 0.f;
; #pragma unroll
;     for (int j = 0; j < 4; ++j) {
;       const float4* w4 = (const float4*)(wl + j * wstride + 16 * hq);
; #pragma unroll
;       for (int q = 0; q < 2; ++q) {
;         float f[8];
;         unpack8(v[j][q], f);
;         float4 wa = w4[2 * q], wb = w4[2 * q + 1];
;         float* a = acc + 16 * hq + 8 * q;
;         a[0] += wa.x * f[0]; a[1] += wa.y * f[1]; a[2] += wa.z * f[2]; a[3] += wa.w * f[3];
;         a[4] += wb.x * f[4]; a[5] += wb.y * f[5]; a[6] += wb.z * f[6]; a[7] += wb.w * f[7];
;       }
;     }
; #pragma unroll
;     for (int i = 0; i < 16; ++i) acc[16 * hq + i] = acc[16 * hq + i] * sigmoidf_(acc[16 * hq + i]);
; DI void mlstm_pre(const Params& p, int ch, char* smem) {
;     ...
;     float a[32];
;     conv32(P + 2048 + h * 128 + part * 32, tok0 + t, c * 64 + t, s_w + part * 32, 256, a);
; #pragma unroll
;     for (int q = 0; q < 4; ++q) *(uint4*)(qs + t * 136 + part * 32 + 8 * q) = pack8(a + 8 * q);
;     {
;       const float sct = s_sc[t];
; #pragma unroll
;       for (int i = 0; i < 32; ++i) a[i] *= sct;
; #pragma unroll
;       for (int q = 0; q < 4; ++q) *(uint4*)(o_q + fragoff(t, part * 32 + 8 * q, 4)) = pack8(a + 8 * q);
;     }
;     conv32(P + 2560 + h * 128 + part * 32, tok0 + t, c * 64 + t, s_w + 128 + part * 32, 256, a);
	v_pk_fma_f32 v[50:51], v[90:91], v[56:57], v[50:51]
	v_lshlrev_b32_e32 v52, 16, v123
	v_and_b32_e32 v53, 0xffff0000, v123
	v_pk_fma_f32 v[46:47], v[60:61], v[48:49], v[46:47]
	s_waitcnt lgkmcnt(0)
	v_pk_fma_f32 v[58:59], v[94:95], v[52:53], v[50:51]
	v_pk_fma_f32 v[46:47], v[92:93], v[54:55], v[46:47]
	v_lshlrev_b32_e32 v48, 16, v122
	v_and_b32_e32 v49, 0xffff0000, v122
	v_pk_mul_f32 v[56:57], v[62:63], v[100:101]
	v_mul_f32_e32 v63, 0xbfb8aa3b, v59
	v_pk_fma_f32 v[54:55], v[96:97], v[48:49], v[46:47]
	v_mul_f32_e32 v50, 0xbfb8aa3b, v58
	v_exp_f32_e32 v63, v63
	v_mul_f32_e32 v46, 0xbfb8aa3b, v54
	v_exp_f32_e32 v85, v50
	v_exp_f32_e32 v46, v46
	v_add_f32_e32 v47, 1.0, v63
	v_rcp_f32_e32 v91, v47
	v_add_f32_e32 v62, 1.0, v85
	v_add_f32_e32 v46, 1.0, v46
	v_mul_f32_e32 v47, 0xbfb8aa3b, v55
	v_rcp_f32_e32 v90, v62
	v_exp_f32_e32 v85, v47
	v_rcp_f32_e32 v92, v46
	ds_read_b128 v[46:49], v84 offset:42096
	ds_read_b128 v[60:63], v84 offset:43120
	ds_read_b128 v[86:89], v84 offset:44144
	v_lshlrev_b32_e32 v44, 16, v18
	v_and_b32_e32 v45, 0xffff0000, v18
	v_lshlrev_b32_e32 v18, 16, v19
	v_and_b32_e32 v19, 0xffff0000, v19
	v_pk_fma_f32 v[2:3], v[2:3], v[18:19], 0 op_sel_hi:[1,1,0]
	v_pk_fma_f32 v[0:1], v[0:1], v[44:45], 0 op_sel_hi:[1,1,0]
	s_waitcnt lgkmcnt(2)
	v_pk_fma_f32 v[2:3], v[48:49], v[20:21], v[2:3]
	v_pk_fma_f32 v[0:1], v[46:47], v[40:41], v[0:1]
	s_waitcnt lgkmcnt(1)
	v_pk_fma_f32 v[2:3], v[62:63], v[36:37], v[2:3]
	v_lshlrev_b32_e32 v18, 16, v64
	v_and_b32_e32 v19, 0xffff0000, v64
	v_pk_fma_f32 v[0:1], v[60:61], v[42:43], v[0:1]
	v_lshlrev_b32_e32 v40, 16, v65
	v_and_b32_e32 v41, 0xffff0000, v65
	s_waitcnt lgkmcnt(0)
	v_pk_fma_f32 v[2:3], v[88:89], v[18:19], v[2:3]
	v_pk_fma_f32 v[0:1], v[86:87], v[40:41], v[0:1]
	v_mul_f32_e32 v18, 0xbfb8aa3b, v2
	v_mul_f32_e32 v19, 0xbfb8aa3b, v3
	v_mul_f32_e32 v40, 0xbfb8aa3b, v0
	v_mul_f32_e32 v41, 0xbfb8aa3b, v1
	v_exp_f32_e32 v18, v18
	v_exp_f32_e32 v19, v19
	v_exp_f32_e32 v40, v40
	v_exp_f32_e32 v41, v41
	v_add_f32_e32 v18, 1.0, v18
	v_add_f32_e32 v19, 1.0, v19
	v_add_f32_e32 v85, 1.0, v85
	v_add_f32_e32 v40, 1.0, v40
	v_add_f32_e32 v41, 1.0, v41
	v_rcp_f32_e32 v18, v18
	v_rcp_f32_e32 v19, v19
	v_rcp_f32_e32 v93, v85
	v_rcp_f32_e32 v40, v40
	v_rcp_f32_e32 v41, v41
	v_pk_mul_f32 v[20:21], v[58:59], v[90:91]
	v_pk_mul_f32 v[18:19], v[2:3], v[18:19]
	v_pk_mul_f32 v[50:51], v[110:111], v[114:115]
	v_pk_mul_f32 v[52:53], v[98:99], v[102:103]
	v_pk_mul_f32 v[36:37], v[54:55], v[92:93]
	v_pk_mul_f32 v[40:41], v[0:1], v[40:41]
	v_mul_lo_u32 v42, v79, s75
	v_add_u32_e32 v85, v42, v28
	v_cvt_pk_bf16_f32 v0, v12, v13
	v_cvt_pk_bf16_f32 v1, v14, v15
	v_cvt_pk_bf16_f32 v2, v16, v17
	v_cvt_pk_bf16_f32 v3, v24, v25
	ds_write_b128 v85, v[0:3]
	v_cvt_pk_bf16_f32 v0, v26, v27
	v_cvt_pk_bf16_f32 v1, v32, v33
	v_cvt_pk_bf16_f32 v2, v34, v35
	v_cvt_pk_bf16_f32 v3, v38, v39
	ds_write_b128 v85, v[0:3] offset:16
	v_cvt_pk_bf16_f32 v0, v22, v23
	v_cvt_pk_bf16_f32 v1, v50, v51
	v_cvt_pk_bf16_f32 v2, v52, v53
	v_cvt_pk_bf16_f32 v3, v56, v57
	ds_write_b128 v85, v[0:3] offset:32
	v_cvt_pk_bf16_f32 v0, v20, v21
	v_cvt_pk_bf16_f32 v1, v36, v37
	v_cvt_pk_bf16_f32 v2, v40, v41
	v_cvt_pk_bf16_f32 v3, v18, v19
	s_movk_i32 s45, 0xfef4
	ds_write_b128 v85, v[0:3] offset:48
	v_mad_u64_u32 v[0:1], s[70:71], v79, s45, v[42:43]
	ds_read_b32 v0, v0 offset:37408
	s_add_u32 s70, s5, s34
	s_addc_u32 s71, s20, 0
	s_waitcnt lgkmcnt(0)
	v_pk_mul_f32 v[2:3], v[12:13], v[0:1] op_sel_hi:[1,0]
	v_pk_mul_f32 v[12:13], v[14:15], v[0:1] op_sel_hi:[1,0]
	v_pk_mul_f32 v[14:15], v[16:17], v[0:1] op_sel_hi:[1,0]
	v_pk_mul_f32 v[16:17], v[24:25], v[0:1] op_sel_hi:[1,0]
	v_pk_mul_f32 v[24:25], v[26:27], v[0:1] op_sel_hi:[1,0]
	v_pk_mul_f32 v[26:27], v[32:33], v[0:1] op_sel_hi:[1,0]
	v_pk_mul_f32 v[32:33], v[34:35], v[0:1] op_sel_hi:[1,0]
	v_pk_mul_f32 v[34:35], v[38:39], v[0:1] op_sel_hi:[1,0]
	v_pk_mul_f32 v[22:23], v[22:23], v[0:1] op_sel_hi:[1,0]
	v_pk_mul_f32 v[38:39], v[50:51], v[0:1] op_sel_hi:[1,0]
	v_pk_mul_f32 v[42:43], v[52:53], v[0:1] op_sel_hi:[1,0]
	v_pk_mul_f32 v[44:45], v[56:57], v[0:1] op_sel_hi:[1,0]
	v_pk_mul_f32 v[20:21], v[20:21], v[0:1] op_sel_hi:[1,0]
	v_pk_mul_f32 v[36:37], v[36:37], v[0:1] op_sel_hi:[1,0]
	v_pk_mul_f32 v[40:41], v[40:41], v[0:1] op_sel_hi:[1,0]
	v_pk_mul_f32 v[18:19], v[18:19], v[0:1] op_sel_hi:[1,0]
	v_lshrrev_b32_e32 v0, 2, v79
	v_lshlrev_b32_e32 v1, 3, v79
	v_and_or_b32 v0, v0, s76, v81
	v_and_b32_e32 v1, 0x78, v1
	v_lshl_or_b32 v46, v0, 9, v1
	v_ashrrev_i32_e32 v47, 31, v46
	v_cvt_pk_bf16_f32 v0, v2, v3
	v_cvt_pk_bf16_f32 v1, v12, v13
	v_cvt_pk_bf16_f32 v2, v14, v15
	v_cvt_pk_bf16_f32 v3, v16, v17
	v_lshl_add_u64 v[12:13], v[46:47], 1, s[60:61]
	global_store_dwordx4 v[12:13], v[0:3], off
	v_lshl_add_u64 v[16:17], s[70:71], 0, v[28:29]
	s_nop 0
	v_cvt_pk_bf16_f32 v0, v24, v25
	v_cvt_pk_bf16_f32 v1, v26, v27
	v_cvt_pk_bf16_f32 v2, v32, v33
	v_cvt_pk_bf16_f32 v3, v34, v35
	global_store_dwordx4 v[12:13], v[0:3], off offset:256
	s_nop 1
	v_cvt_pk_bf16_f32 v0, v22, v23
	v_cvt_pk_bf16_f32 v1, v38, v39
	v_cvt_pk_bf16_f32 v2, v42, v43
	v_cvt_pk_bf16_f32 v3, v44, v45
	global_store_dwordx4 v[12:13], v[0:3], off offset:512
	s_nop 1
	v_cvt_pk_bf16_f32 v0, v20, v21
	v_cvt_pk_bf16_f32 v1, v36, v37
	v_cvt_pk_bf16_f32 v2, v40, v41
	v_cvt_pk_bf16_f32 v3, v18, v19
	global_store_dwordx4 v[12:13], v[0:3], off offset:768
	v_lshl_add_u64 v[10:11], v[16:17], 0, v[10:11]
	global_load_dwordx4 v[0:3], v[10:11], off offset:16
	global_load_dwordx4 v[12:15], v[10:11], off
	v_lshl_add_u64 v[6:7], v[16:17], 0, v[6:7]
	v_lshl_add_u64 v[4:5], v[16:17], 0, v[4:5]
	s_waitcnt vmcnt(1)
	v_cndmask_b32_e64 v24, 0, v3, s[10:11]
	s_waitcnt vmcnt(0)
; DI void conv32(const bf16_t* __restrict__ Pcol, int tok, int spos, const float* wl, int wstride, float* acc) {
; #pragma unroll
;   for (int hq = 0; hq < 2; ++hq) {
;     __builtin_amdgcn_sched_barrier(0);
;     uint4 v[4][2];
; #pragma unroll
;     for (int j = 0; j < 4; ++j) {
;       const bool ok = (spos - 3 + j >= 0);
;       const uint4* src = (const uint4*)(Pcol + (size_t)(tok - 3 + (ok ? j : 3)) * 4096) + 2 * hq;
; #pragma unroll
;       for (int q = 0; q < 2; ++q) {
;         v[j][q] = src[q];
;         if (!ok) v[j][q] = make_uint4(0u, 0u, 0u, 0u);
;       }
;     }
; #pragma unroll
;     for (int i = 0; i < 16; ++i) acc[16 * hq + i] = 0.f;
; #pragma unroll
;     for (int j = 0; j < 4; ++j) {
;       const float4* w4 = (const float4*)(wl + j * wstride + 16 * hq);
; #pragma unroll
;       for (int q = 0; q < 2; ++q) {
;         float f[8];
;         unpack8(v[j][q], f);
;         float4 wa = w4[2 * q], wb = w4[2 * q + 1];
;         float* a = acc + 16 * hq + 8 * q;
;         a[0] += wa.x * f[0]; a[1] += wa.y * f[1]; a[2] += wa.z * f[2]; a[3] += wa.w * f[3];
;         a[4] += wb.x * f[4]; a[5] += wb.y * f[5]; a[6] += wb.z * f[6]; a[7] += wb.w * f[7];
;       }
;     }
	v_cndmask_b32_e64 v20, 0, v15, s[10:11]
	v_cndmask_b32_e64 v21, 0, v14, s[10:11]
	v_cndmask_b32_e64 v23, 0, v13, s[10:11]
	v_cndmask_b32_e64 v19, 0, v12, s[10:11]
	v_cndmask_b32_e64 v25, 0, v2, s[10:11]
	v_cndmask_b32_e64 v26, 0, v1, s[10:11]
	v_cndmask_b32_e64 v27, 0, v0, s[10:11]
	global_load_dwordx4 v[0:3], v[6:7], off offset:16
	global_load_dwordx4 v[12:15], v[6:7], off
	v_lshlrev_b32_e32 v56, 16, v27
	v_and_b32_e32 v57, 0xffff0000, v27
	v_lshlrev_b32_e32 v58, 16, v26
	v_and_b32_e32 v59, 0xffff0000, v26
	v_lshlrev_b32_e32 v60, 16, v25
	v_and_b32_e32 v61, 0xffff0000, v25
	v_lshlrev_b32_e32 v18, 16, v19
	v_and_b32_e32 v19, 0xffff0000, v19
	v_lshlrev_b32_e32 v52, 16, v21
	v_and_b32_e32 v53, 0xffff0000, v21
	v_lshlrev_b32_e32 v54, 16, v20
	v_and_b32_e32 v55, 0xffff0000, v20
	v_lshlrev_b32_e32 v22, 16, v23
	v_and_b32_e32 v23, 0xffff0000, v23
	s_waitcnt vmcnt(1)
	v_cndmask_b32_e64 v36, 0, v3, s[12:13]
	s_waitcnt vmcnt(0)
	v_cndmask_b32_e64 v32, 0, v15, s[12:13]
	v_cndmask_b32_e64 v33, 0, v14, s[12:13]
	v_cndmask_b32_e64 v34, 0, v13, s[12:13]
	v_cndmask_b32_e64 v35, 0, v12, s[12:13]
	v_cndmask_b32_e64 v37, 0, v2, s[12:13]
	v_cndmask_b32_e64 v38, 0, v1, s[12:13]
	v_cndmask_b32_e64 v39, 0, v0, s[12:13]
	global_load_dwordx4 v[0:3], v[4:5], off offset:16
	global_load_dwordx4 v[12:15], v[4:5], off
	v_lshlrev_b32_e32 v44, 16, v35
	v_and_b32_e32 v45, 0xffff0000, v35
	v_lshlrev_b32_e32 v62, 16, v34
	v_and_b32_e32 v63, 0xffff0000, v34
	v_lshlrev_b32_e32 v64, 16, v33
	v_and_b32_e32 v65, 0xffff0000, v33
	v_lshlrev_b32_e32 v86, 16, v32
	v_and_b32_e32 v87, 0xffff0000, v32
	v_lshlrev_b32_e32 v88, 16, v39
	v_and_b32_e32 v89, 0xffff0000, v39
	v_lshlrev_b32_e32 v90, 16, v38
	v_and_b32_e32 v91, 0xffff0000, v38
	v_lshlrev_b32_e32 v92, 16, v37
	v_and_b32_e32 v93, 0xffff0000, v37
	s_waitcnt vmcnt(1)
	v_cndmask_b32_e64 v46, 0, v3, s[14:15]
	s_waitcnt vmcnt(0)
	v_cndmask_b32_e64 v42, 0, v13, s[14:15]
	v_cndmask_b32_e64 v43, 0, v12, s[14:15]
	v_lshl_add_u64 v[12:13], v[16:17], 0, v[8:9]
	v_cndmask_b32_e64 v40, 0, v15, s[14:15]
	v_cndmask_b32_e64 v41, 0, v14, s[14:15]
	v_cndmask_b32_e64 v47, 0, v2, s[14:15]
	v_cndmask_b32_e64 v50, 0, v1, s[14:15]
	v_cndmask_b32_e64 v51, 0, v0, s[14:15]
	global_load_dwordx4 v[0:3], v[12:13], off offset:16
	global_load_dwordx4 v[14:17], v[12:13], off
	v_lshlrev_b32_e32 v48, 16, v43
	v_and_b32_e32 v49, 0xffff0000, v43
	v_lshlrev_b32_e32 v94, 16, v42
	v_and_b32_e32 v95, 0xffff0000, v42
	v_lshlrev_b32_e32 v96, 16, v41
	v_and_b32_e32 v97, 0xffff0000, v41
	v_lshlrev_b32_e32 v98, 16, v40
	v_and_b32_e32 v99, 0xffff0000, v40
	v_lshlrev_b32_e32 v104, 16, v47
	v_and_b32_e32 v105, 0xffff0000, v47
	v_lshlrev_b32_e32 v20, 16, v46
	v_and_b32_e32 v21, 0xffff0000, v46
	v_lshlrev_b32_e32 v100, 16, v51
	v_and_b32_e32 v101, 0xffff0000, v51
	v_lshlrev_b32_e32 v102, 16, v50
	v_and_b32_e32 v103, 0xffff0000, v50
	s_waitcnt vmcnt(1)
	v_cndmask_b32_e64 v114, 0, v3, s[8:9]
	s_waitcnt vmcnt(0)
	v_cndmask_b32_e64 v113, 0, v17, s[8:9]
	v_cndmask_b32_e64 v111, 0, v16, s[8:9]
	v_cndmask_b32_e64 v109, 0, v15, s[8:9]
	v_cndmask_b32_e64 v107, 0, v14, s[8:9]
	v_cndmask_b32_e64 v115, 0, v2, s[8:9]
	v_cndmask_b32_e64 v116, 0, v1, s[8:9]
	v_cndmask_b32_e64 v117, 0, v0, s[8:9]
	v_lshlrev_b32_e32 v14, 16, v24
	v_and_b32_e32 v15, 0xffff0000, v24
	v_lshlrev_b32_e32 v16, 16, v36
	v_and_b32_e32 v17, 0xffff0000, v36
	ds_read_b128 v[24:27], v84 offset:41472
	ds_read_b128 v[32:35], v84 offset:41488
	ds_read_b128 v[36:39], v84 offset:41504
	ds_read_b128 v[0:3], v84 offset:41520
	ds_read_b128 v[40:43], v84 offset:42496
	s_waitcnt lgkmcnt(4)
	v_pk_fma_f32 v[18:19], v[24:25], v[18:19], 0 op_sel_hi:[1,1,0]
	v_lshlrev_b32_e32 v106, 16, v107
	v_and_b32_e32 v107, 0xffff0000, v107
	v_lshlrev_b32_e32 v108, 16, v109
	s_waitcnt lgkmcnt(0)
	v_pk_fma_f32 v[18:19], v[40:41], v[44:45], v[18:19]
	ds_read_b128 v[44:47], v84 offset:43520
	v_and_b32_e32 v109, 0xffff0000, v109
	v_lshlrev_b32_e32 v110, 16, v111
	v_and_b32_e32 v111, 0xffff0000, v111
	v_pk_fma_f32 v[36:37], v[36:37], v[56:57], 0 op_sel_hi:[1,1,0]
	s_waitcnt lgkmcnt(0)
	v_pk_fma_f32 v[18:19], v[44:45], v[48:49], v[18:19]
	ds_read_b128 v[48:51], v84 offset:44544
	v_lshlrev_b32_e32 v112, 16, v113
	v_and_b32_e32 v113, 0xffff0000, v113
	v_pk_fma_f32 v[0:1], v[0:1], v[60:61], 0 op_sel_hi:[1,1,0]
	s_waitcnt lgkmcnt(0)
	v_pk_fma_f32 v[24:25], v[48:49], v[106:107], v[18:19]
	v_pk_fma_f32 v[18:19], v[26:27], v[22:23], 0 op_sel_hi:[1,1,0]
	v_pk_fma_f32 v[22:23], v[32:33], v[52:53], 0 op_sel_hi:[1,1,0]
	v_pk_fma_f32 v[18:19], v[42:43], v[62:63], v[18:19]
	ds_read_b128 v[40:43], v84 offset:42512
	v_pk_fma_f32 v[18:19], v[46:47], v[94:95], v[18:19]
	ds_read_b128 v[44:47], v84 offset:43536
	v_pk_fma_f32 v[18:19], v[50:51], v[108:109], v[18:19]
	ds_read_b128 v[48:51], v84 offset:44560
	s_waitcnt lgkmcnt(2)
	v_pk_fma_f32 v[22:23], v[40:41], v[64:65], v[22:23]
	v_lshlrev_b32_e32 v52, 16, v115
	s_waitcnt lgkmcnt(1)
	v_pk_fma_f32 v[22:23], v[44:45], v[96:97], v[22:23]
	v_and_b32_e32 v53, 0xffff0000, v115
	s_waitcnt lgkmcnt(0)
	v_pk_fma_f32 v[26:27], v[48:49], v[110:111], v[22:23]
	v_pk_fma_f32 v[22:23], v[34:35], v[54:55], 0 op_sel_hi:[1,1,0]
	ds_read_b128 v[32:35], v84 offset:42528
	v_pk_fma_f32 v[22:23], v[42:43], v[86:87], v[22:23]
	ds_read_b128 v[40:43], v84 offset:43552
	v_pk_fma_f32 v[22:23], v[46:47], v[98:99], v[22:23]
	ds_read_b128 v[44:47], v84 offset:44576
	s_waitcnt lgkmcnt(2)
	v_pk_fma_f32 v[32:33], v[32:33], v[88:89], v[36:37]
	v_pk_fma_f32 v[48:49], v[50:51], v[112:113], v[22:23]
	v_lshlrev_b32_e32 v22, 16, v117
	v_and_b32_e32 v23, 0xffff0000, v117
	s_waitcnt lgkmcnt(1)
	v_pk_fma_f32 v[32:33], v[40:41], v[100:101], v[32:33]
	v_lshlrev_b32_e32 v54, 16, v114
	s_waitcnt lgkmcnt(0)
; DI float sigmoidf_(float x) { return __builtin_amdgcn_rcpf(1.f + __expf(-x)); }
; DI void conv32(const bf16_t* __restrict__ Pcol, int tok, int spos, const float* wl, int wstride, float* acc) {
;     ...
; #pragma unroll
;     for (int j = 0; j < 4; ++j) {
;       const bool ok = (spos - 3 + j >= 0);
;       const uint4* src = (const uint4*)(Pcol + (size_t)(tok - 3 + (ok ? j : 3)) * 4096) + 2 * hq;
; #pragma unroll
;       for (int q = 0; q < 2; ++q) {
;         v[j][q] = src[q];
;         if (!ok) v[j][q] = make_uint4(0u, 0u, 0u, 0u);
;       }
;     }
; #pragma unroll
;     for (int i = 0; i < 16; ++i) acc[16 * hq + i] = 0.f;
; #pragma unroll
;     for (int j = 0; j < 4; ++j) {
;       const float4* w4 = (const float4*)(wl + j * wstride + 16 * hq);
; #pragma unroll
;       for (int q = 0; q < 2; ++q) {
;         float f[8];
;         unpack8(v[j][q], f);
;         float4 wa = w4[2 * q], wb = w4[2 * q + 1];
;         float* a = acc + 16 * hq + 8 * q;
;         a[0] += wa.x * f[0]; a[1] += wa.y * f[1]; a[2] += wa.z * f[2]; a[3] += wa.w * f[3];
;         a[4] += wb.x * f[4]; a[5] += wb.y * f[5]; a[6] += wb.z * f[6]; a[7] += wb.w * f[7];
;       }
;     }
; #pragma unroll
;     for (int i = 0; i < 16; ++i) acc[16 * hq + i] = acc[16 * hq + i] * sigmoidf_(acc[16 * hq + i]);
;   }
; DI void mlstm_pre(const Params& p, int ch, char* smem) {
;     ...
;     for (int i = 0; i < 32; ++i) a[i] *= 0.08838834764831845f;
	v_pk_fma_f32 v[44:45], v[44:45], v[22:23], v[32:33]
	v_pk_fma_f32 v[22:23], v[38:39], v[58:59], 0 op_sel_hi:[1,1,0]
	ds_read_b128 v[36:39], v84 offset:43568
	v_pk_fma_f32 v[22:23], v[34:35], v[90:91], v[22:23]
	ds_read_b128 v[32:35], v84 offset:42544
	v_pk_fma_f32 v[22:23], v[42:43], v[102:103], v[22:23]
	ds_read_b128 v[40:43], v84 offset:44592
	v_and_b32_e32 v55, 0xffff0000, v114
	v_lshlrev_b32_e32 v50, 16, v116
	s_waitcnt lgkmcnt(1)
	v_pk_fma_f32 v[0:1], v[32:33], v[92:93], v[0:1]
	v_and_b32_e32 v51, 0xffff0000, v116
	v_pk_fma_f32 v[0:1], v[36:37], v[104:105], v[0:1]
	v_pk_fma_f32 v[22:23], v[46:47], v[50:51], v[22:23]
	s_waitcnt lgkmcnt(0)
	v_pk_fma_f32 v[32:33], v[40:41], v[52:53], v[0:1]
	v_pk_fma_f32 v[0:1], v[2:3], v[14:15], 0 op_sel_hi:[1,1,0]
	v_mul_f32_e32 v2, 0xbfb8aa3b, v18
	v_pk_fma_f32 v[0:1], v[34:35], v[16:17], v[0:1]
	v_mul_f32_e32 v3, 0xbfb8aa3b, v19
	v_pk_fma_f32 v[0:1], v[38:39], v[20:21], v[0:1]
	v_exp_f32_e32 v2, v2
	v_pk_fma_f32 v[20:21], v[42:43], v[54:55], v[0:1]
	v_mul_f32_e32 v0, 0xbfb8aa3b, v24
	v_mul_f32_e32 v1, 0xbfb8aa3b, v25
	v_exp_f32_e32 v0, v0
	v_exp_f32_e32 v1, v1
	v_exp_f32_e32 v3, v3
	v_add_f32_e32 v2, 1.0, v2
	v_add_f32_e32 v0, 1.0, v0
	v_add_f32_e32 v1, 1.0, v1
	v_rcp_f32_e32 v0, v0
	v_rcp_f32_e32 v1, v1
	v_add_f32_e32 v3, 1.0, v3
	v_rcp_f32_e32 v2, v2
	v_rcp_f32_e32 v3, v3
	v_pk_mul_f32 v[0:1], v[24:25], v[0:1]
	v_mul_f32_e32 v24, 0xbfb8aa3b, v22
	v_mul_f32_e32 v25, 0xbfb8aa3b, v23
	v_exp_f32_e32 v24, v24
	v_exp_f32_e32 v25, v25
	v_pk_mul_f32 v[2:3], v[18:19], v[2:3]
	v_mul_f32_e32 v14, 0xbfb8aa3b, v26
	v_add_f32_e32 v24, 1.0, v24
	v_add_f32_e32 v25, 1.0, v25
	v_rcp_f32_e32 v24, v24
	v_rcp_f32_e32 v25, v25
	v_mul_f32_e32 v15, 0xbfb8aa3b, v27
	v_mul_f32_e32 v16, 0xbfb8aa3b, v48
	v_mul_f32_e32 v17, 0xbfb8aa3b, v49
	v_pk_mul_f32 v[64:65], v[22:23], v[24:25]
	v_mul_f32_e32 v22, 0xbfb8aa3b, v32
	v_mul_f32_e32 v23, 0xbfb8aa3b, v33
	v_exp_f32_e32 v22, v22
	v_exp_f32_e32 v23, v23
	v_mul_f32_e32 v18, 0xbfb8aa3b, v44
	v_mul_f32_e32 v19, 0xbfb8aa3b, v45
	v_add_f32_e32 v22, 1.0, v22
	v_add_f32_e32 v23, 1.0, v23
	v_rcp_f32_e32 v22, v22
	v_rcp_f32_e32 v23, v23
	v_exp_f32_e32 v14, v14
	v_exp_f32_e32 v15, v15
	v_exp_f32_e32 v16, v16
	v_exp_f32_e32 v17, v17
	v_exp_f32_e32 v18, v18
	v_exp_f32_e32 v19, v19
	v_pk_mul_f32 v[88:89], v[32:33], v[22:23]
	v_mul_f32_e32 v22, 0xbfb8aa3b, v20
	v_mul_f32_e32 v23, 0xbfb8aa3b, v21
	v_exp_f32_e32 v22, v22
	v_exp_f32_e32 v23, v23
	v_add_f32_e32 v14, 1.0, v14
	v_add_f32_e32 v15, 1.0, v15
	v_add_f32_e32 v16, 1.0, v16
	v_add_f32_e32 v17, 1.0, v17
	v_add_f32_e32 v18, 1.0, v18
	v_add_f32_e32 v19, 1.0, v19
	v_rcp_f32_e32 v14, v14
	v_rcp_f32_e32 v15, v15
	v_rcp_f32_e32 v16, v16
	v_rcp_f32_e32 v17, v17
	v_rcp_f32_e32 v18, v18
	v_rcp_f32_e32 v19, v19
	v_add_f32_e32 v22, 1.0, v22
	v_add_f32_e32 v23, 1.0, v23
	v_rcp_f32_e32 v22, v22
	v_rcp_f32_e32 v23, v23
	v_pk_mul_f32 v[14:15], v[26:27], v[14:15]
	v_pk_mul_f32 v[16:17], v[48:49], v[16:17]
	v_pk_mul_f32 v[18:19], v[44:45], v[18:19]
	v_pk_mul_f32 v[90:91], v[20:21], v[22:23]
	global_load_dwordx4 v[20:23], v[10:11], off offset:32
	global_load_dwordx4 v[24:27], v[10:11], off offset:48
	global_load_dwordx4 v[32:35], v[6:7], off offset:32
	global_load_dwordx4 v[36:39], v[6:7], off offset:48
	global_load_dwordx4 v[40:43], v[4:5], off offset:32
	s_nop 0
	global_load_dwordx4 v[4:7], v[4:5], off offset:48
	s_nop 0
	global_load_dwordx4 v[44:47], v[12:13], off offset:32
	s_nop 0
	global_load_dwordx4 v[10:13], v[12:13], off offset:48
	v_pk_mul_f32 v[18:19], v[18:19], s[36:37] op_sel_hi:[1,0]
	s_waitcnt vmcnt(7)
	v_cndmask_b32_e64 v20, 0, v20, s[10:11]
	s_waitcnt vmcnt(6)
	v_cndmask_b32_e64 v27, 0, v27, s[10:11]
	v_cndmask_b32_e64 v26, 0, v26, s[10:11]
	v_cndmask_b32_e64 v25, 0, v25, s[10:11]
	v_cndmask_b32_e64 v24, 0, v24, s[10:11]
	s_waitcnt vmcnt(5)
	v_cndmask_b32_e64 v52, 0, v35, s[12:13]
	v_cndmask_b32_e64 v53, 0, v34, s[12:13]
	v_cndmask_b32_e64 v54, 0, v33, s[12:13]
	v_cndmask_b32_e64 v55, 0, v32, s[12:13]
	s_waitcnt vmcnt(4)
	v_cndmask_b32_e64 v56, 0, v39, s[12:13]
	v_cndmask_b32_e64 v57, 0, v38, s[12:13]
	v_cndmask_b32_e64 v37, 0, v37, s[12:13]
	v_cndmask_b32_e64 v36, 0, v36, s[12:13]
	s_waitcnt vmcnt(3)
	v_cndmask_b32_e64 v41, 0, v41, s[14:15]
	v_cndmask_b32_e64 v40, 0, v40, s[14:15]
	s_waitcnt vmcnt(2)
	v_cndmask_b32_e64 v62, 0, v7, s[14:15]
	v_cndmask_b32_e64 v63, 0, v6, s[14:15]
	v_cndmask_b32_e64 v92, 0, v5, s[14:15]
	v_cndmask_b32_e64 v93, 0, v4, s[14:15]
	s_waitcnt vmcnt(1)
	v_cndmask_b32_e64 v94, 0, v47, s[8:9]
	v_cndmask_b32_e64 v95, 0, v46, s[8:9]
	v_cndmask_b32_e64 v96, 0, v45, s[8:9]
	v_cndmask_b32_e64 v97, 0, v44, s[8:9]
	v_cndmask_b32_e64 v61, 0, v43, s[14:15]
	v_cndmask_b32_e64 v60, 0, v42, s[14:15]
	s_waitcnt vmcnt(0)
; DI float sigmoidf_(float x) { return __builtin_amdgcn_rcpf(1.f + __expf(-x)); }
; DI void conv32(const bf16_t* __restrict__ Pcol, int tok, int spos, const float* wl, int wstride, float* acc) {
;     ...
; #pragma unroll
;     for (int j = 0; j < 4; ++j) {
;       const bool ok = (spos - 3 + j >= 0);
;       const uint4* src = (const uint4*)(Pcol + (size_t)(tok - 3 + (ok ? j : 3)) * 4096) + 2 * hq;
; #pragma unroll
;       for (int q = 0; q < 2; ++q) {
;         v[j][q] = src[q];
;         if (!ok) v[j][q] = make_uint4(0u, 0u, 0u, 0u);
;       }
;     }
; #pragma unroll
;     for (int i = 0; i < 16; ++i) acc[16 * hq + i] = 0.f;
; #pragma unroll
;     for (int j = 0; j < 4; ++j) {
;       const float4* w4 = (const float4*)(wl + j * wstride + 16 * hq);
; #pragma unroll
;       for (int q = 0; q < 2; ++q) {
;         float f[8];
;         unpack8(v[j][q], f);
;         float4 wa = w4[2 * q], wb = w4[2 * q + 1];
;         float* a = acc + 16 * hq + 8 * q;
;         a[0] += wa.x * f[0]; a[1] += wa.y * f[1]; a[2] += wa.z * f[2]; a[3] += wa.w * f[3];
;         a[4] += wb.x * f[4]; a[5] += wb.y * f[5]; a[6] += wb.z * f[6]; a[7] += wb.w * f[7];
;       }
;     }
; #pragma unroll
;     for (int i = 0; i < 16; ++i) acc[16 * hq + i] = acc[16 * hq + i] * sigmoidf_(acc[16 * hq + i]);
;   }
; DI void mlstm_pre(const Params& p, int ch, char* smem) {
;     ...
;     for (int i = 0; i < 32; ++i) a[i] *= 0.08838834764831845f;
	v_cndmask_b32_e64 v86, 0, v13, s[8:9]
	v_cndmask_b32_e64 v87, 0, v12, s[8:9]
	v_cndmask_b32_e64 v124, 0, v11, s[8:9]
	v_cndmask_b32_e64 v125, 0, v10, s[8:9]
	v_lshlrev_b32_e32 v4, 16, v20
	v_and_b32_e32 v5, 0xffff0000, v20
	v_lshlrev_b32_e32 v38, 16, v24
	v_and_b32_e32 v39, 0xffff0000, v24
	v_lshlrev_b32_e32 v50, 16, v25
	v_and_b32_e32 v51, 0xffff0000, v25
	v_lshlrev_b32_e32 v48, 16, v26
	v_and_b32_e32 v49, 0xffff0000, v26
	v_lshlrev_b32_e32 v32, 16, v27
	v_and_b32_e32 v33, 0xffff0000, v27
	v_lshlrev_b32_e32 v6, 16, v55
	v_and_b32_e32 v7, 0xffff0000, v55
	v_lshlrev_b32_e32 v108, 16, v54
	v_and_b32_e32 v109, 0xffff0000, v54
	v_lshlrev_b32_e32 v110, 16, v53
	v_and_b32_e32 v111, 0xffff0000, v53
	v_lshlrev_b32_e32 v58, 16, v52
	v_and_b32_e32 v59, 0xffff0000, v52
	v_lshlrev_b32_e32 v42, 16, v36
	v_and_b32_e32 v43, 0xffff0000, v36
	v_lshlrev_b32_e32 v52, 16, v37
	v_and_b32_e32 v53, 0xffff0000, v37
	v_lshlrev_b32_e32 v44, 16, v57
	v_and_b32_e32 v45, 0xffff0000, v57
	v_lshlrev_b32_e32 v36, 16, v56
	v_and_b32_e32 v37, 0xffff0000, v56
	v_lshlrev_b32_e32 v112, 16, v40
	v_and_b32_e32 v113, 0xffff0000, v40
	v_lshlrev_b32_e32 v114, 16, v41
	v_and_b32_e32 v115, 0xffff0000, v41
	v_lshlrev_b32_e32 v56, 16, v93
	v_and_b32_e32 v57, 0xffff0000, v93
	v_lshlrev_b32_e32 v54, 16, v92
	v_and_b32_e32 v55, 0xffff0000, v92
	v_lshlrev_b32_e32 v46, 16, v63
	v_and_b32_e32 v47, 0xffff0000, v63
	v_lshlrev_b32_e32 v40, 16, v62
	v_and_b32_e32 v41, 0xffff0000, v62
	v_lshlrev_b32_e32 v118, 16, v97
	v_and_b32_e32 v119, 0xffff0000, v97
	v_lshlrev_b32_e32 v120, 16, v96
	v_and_b32_e32 v121, 0xffff0000, v96
	v_lshlrev_b32_e32 v122, 16, v95
	v_and_b32_e32 v123, 0xffff0000, v95
	v_lshlrev_b32_e32 v62, 16, v94
	v_and_b32_e32 v63, 0xffff0000, v94
	v_pk_mul_f32 v[26:27], v[0:1], s[36:37] op_sel_hi:[1,0]
	v_pk_mul_f32 v[24:25], v[2:3], s[36:37] op_sel_hi:[1,0]
	v_pk_mul_f32 v[12:13], v[88:89], s[36:37] op_sel_hi:[1,0]
	v_pk_mul_f32 v[10:11], v[90:91], s[36:37] op_sel_hi:[1,0]
	ds_read_b128 v[0:3], v84 offset:41536
	ds_read_b128 v[88:91], v84 offset:42560
	ds_read_b128 v[92:95], v84 offset:43584
	ds_read_b128 v[96:99], v84 offset:44608
	ds_read_b128 v[100:103], v84 offset:41552
	s_waitcnt lgkmcnt(4)
	v_pk_fma_f32 v[0:1], v[0:1], v[4:5], 0 op_sel_hi:[1,1,0]
	v_cndmask_b32_e64 v23, 0, v23, s[10:11]
	s_waitcnt lgkmcnt(3)
	v_pk_fma_f32 v[0:1], v[88:89], v[6:7], v[0:1]
	v_cndmask_b32_e64 v22, 0, v22, s[10:11]
	s_waitcnt lgkmcnt(2)
	v_pk_fma_f32 v[0:1], v[92:93], v[112:113], v[0:1]
	v_lshlrev_b32_e32 v106, 16, v22
	v_and_b32_e32 v107, 0xffff0000, v22
	v_lshlrev_b32_e32 v34, 16, v23
	v_and_b32_e32 v35, 0xffff0000, v23
	v_pk_mul_f32 v[22:23], v[14:15], s[36:37] op_sel_hi:[1,0]
	s_waitcnt lgkmcnt(1)
	v_pk_fma_f32 v[14:15], v[96:97], v[118:119], v[0:1]
	v_cndmask_b32_e64 v21, 0, v21, s[10:11]
	v_mul_f32_e32 v0, 0xbfb8aa3b, v14
	v_exp_f32_e32 v0, v0
	v_mul_f32_e32 v1, 0xbfb8aa3b, v15
	v_exp_f32_e32 v1, v1
	v_lshlrev_b32_e32 v104, 16, v21
	v_add_f32_e32 v0, 1.0, v0
	v_and_b32_e32 v105, 0xffff0000, v21
	v_pk_mul_f32 v[20:21], v[16:17], s[36:37] op_sel_hi:[1,0]
	v_pk_mul_f32 v[16:17], v[64:65], s[36:37] op_sel_hi:[1,0]
	v_rcp_f32_e32 v64, v0
	v_add_f32_e32 v0, 1.0, v1
	v_rcp_f32_e32 v65, v0
	v_pk_fma_f32 v[0:1], v[2:3], v[104:105], 0 op_sel_hi:[1,1,0]
	ds_read_b128 v[4:7], v84 offset:41568
	v_pk_fma_f32 v[0:1], v[90:91], v[108:109], v[0:1]
	v_pk_mul_f32 v[14:15], v[14:15], v[64:65]
	v_pk_fma_f32 v[0:1], v[94:95], v[114:115], v[0:1]
	s_waitcnt lgkmcnt(1)
	v_pk_fma_f32 v[100:101], v[100:101], v[106:107], 0 op_sel_hi:[1,1,0]
	v_pk_fma_f32 v[104:105], v[98:99], v[120:121], v[0:1]
	v_lshlrev_b32_e32 v116, 16, v60
	v_mul_f32_e32 v0, 0xbfb8aa3b, v104
	v_exp_f32_e32 v88, v0
	ds_read_b128 v[0:3], v84 offset:41584
	v_and_b32_e32 v117, 0xffff0000, v60
	v_mul_f32_e32 v65, 0xbfb8aa3b, v105
	v_add_f32_e32 v64, 1.0, v88
	ds_read_b128 v[88:91], v84 offset:42576
	ds_read_b128 v[92:95], v84 offset:43600
	ds_read_b128 v[96:99], v84 offset:44624
	v_pk_fma_f32 v[34:35], v[102:103], v[34:35], 0 op_sel_hi:[1,1,0]
	v_lshlrev_b32_e32 v60, 16, v61
	s_waitcnt lgkmcnt(2)
	v_pk_fma_f32 v[88:89], v[88:89], v[110:111], v[100:101]
	v_and_b32_e32 v61, 0xffff0000, v61
	s_waitcnt lgkmcnt(1)
	v_pk_fma_f32 v[88:89], v[92:93], v[116:117], v[88:89]
	v_exp_f32_e32 v65, v65
	s_waitcnt lgkmcnt(0)
	v_pk_fma_f32 v[88:89], v[96:97], v[122:123], v[88:89]
	v_pk_fma_f32 v[34:35], v[90:91], v[58:59], v[34:35]
	v_mul_f32_e32 v92, 0xbfb8aa3b, v88
	v_mul_f32_e32 v93, 0xbfb8aa3b, v89
	v_exp_f32_e32 v92, v92
	v_exp_f32_e32 v93, v93
	v_pk_fma_f32 v[34:35], v[94:95], v[60:61], v[34:35]
	v_add_f32_e32 v65, 1.0, v65
	v_add_f32_e32 v92, 1.0, v92
	v_add_f32_e32 v93, 1.0, v93
	v_rcp_f32_e32 v92, v92
	v_rcp_f32_e32 v93, v93
	v_pk_fma_f32 v[94:95], v[98:99], v[62:63], v[34:35]
	v_rcp_f32_e32 v64, v64
	v_mul_f32_e32 v34, 0xbfb8aa3b, v94
	v_exp_f32_e32 v58, v34
	v_rcp_f32_e32 v65, v65
	v_mul_f32_e32 v59, 0xbfb8aa3b, v95
	v_pk_mul_f32 v[92:93], v[88:89], v[92:93]
	v_exp_f32_e32 v88, v59
	v_add_f32_e32 v58, 1.0, v58
	v_pk_mul_f32 v[34:35], v[104:105], v[64:65]
	v_rcp_f32_e32 v96, v58
	ds_read_b128 v[58:61], v84 offset:42592
	ds_read_b128 v[62:65], v84 offset:43616
	v_add_f32_e32 v97, 1.0, v88
	ds_read_b128 v[88:91], v84 offset:44640
	v_pk_fma_f32 v[4:5], v[4:5], v[38:39], 0 op_sel_hi:[1,1,0]
	v_lshlrev_b32_e32 v38, 16, v125
	s_waitcnt lgkmcnt(2)
	v_pk_fma_f32 v[4:5], v[58:59], v[42:43], v[4:5]
	v_and_b32_e32 v39, 0xffff0000, v125
	s_waitcnt lgkmcnt(1)
	v_pk_fma_f32 v[4:5], v[62:63], v[56:57], v[4:5]
	v_pk_fma_f32 v[6:7], v[6:7], v[50:51], 0 op_sel_hi:[1,1,0]
	s_waitcnt lgkmcnt(0)
; DI bf16_t f2bf(float f) { return (bf16_t)(pk2(f, 0.f) & 0xffffu); }
; DI float bf2f(bf16_t h) { return __uint_as_float(((unsigned)h) << 16); }
; DI int fragoff(int row, int k, int KS) { return (((row >> 4) * KS + (k >> 5)) << 9) + (((((k >> 3) & 3) << 4) + (row & 15)) << 3) + (k & 7); }
; DI void mlstm_pre(const Params& p, int ch, char* smem) {
;     ...
;     for (int i = 0; i < 32; ++i) a[i] *= 0.08838834764831845f;
; #pragma unroll
;     for (int q = 0; q < 4; ++q) *(uint4*)(ks + t * 136 + part * 32 + 8 * q) = pack8(a + 8 * q);
; #pragma unroll
;     for (int i = 0; i < 32; ++i) {
;       bf16_t kb = f2bf(a[i] * wgt);
;       o_kwT[fragoff(part * 32 + i, t, 2)] = kb;
;       atomicAdd(&s_kw[part * 32 + i], bf2f(kb));
	v_pk_fma_f32 v[4:5], v[88:89], v[38:39], v[4:5]
	v_pk_fma_f32 v[6:7], v[60:61], v[52:53], v[6:7]
	v_mul_f32_e32 v38, 0xbfb8aa3b, v4
	v_exp_f32_e32 v38, v38
	v_mul_f32_e32 v39, 0xbfb8aa3b, v5
	v_exp_f32_e32 v39, v39
	v_pk_fma_f32 v[6:7], v[64:65], v[54:55], v[6:7]
	v_lshlrev_b32_e32 v50, 16, v124
	v_and_b32_e32 v51, 0xffff0000, v124
	v_pk_fma_f32 v[6:7], v[90:91], v[50:51], v[6:7]
	v_add_f32_e32 v38, 1.0, v38
	v_mul_f32_e32 v50, 0xbfb8aa3b, v6
	v_rcp_f32_e32 v56, v38
	v_add_f32_e32 v38, 1.0, v39
	v_exp_f32_e32 v50, v50
	v_mul_f32_e32 v51, 0xbfb8aa3b, v7
	v_rcp_f32_e32 v57, v38
	v_exp_f32_e32 v51, v51
	v_add_f32_e32 v50, 1.0, v50
	v_rcp_f32_e32 v62, v50
	v_pk_mul_f32 v[4:5], v[4:5], v[56:57]
	v_add_f32_e32 v58, 1.0, v51
	ds_read_b128 v[50:53], v84 offset:42608
	ds_read_b128 v[54:57], v84 offset:43632
	v_rcp_f32_e32 v63, v58
	ds_read_b128 v[58:61], v84 offset:44656
	v_pk_fma_f32 v[0:1], v[0:1], v[48:49], 0 op_sel_hi:[1,1,0]
	v_pk_fma_f32 v[2:3], v[2:3], v[32:33], 0 op_sel_hi:[1,1,0]
	s_waitcnt lgkmcnt(2)
	v_pk_fma_f32 v[0:1], v[50:51], v[44:45], v[0:1]
	v_pk_fma_f32 v[2:3], v[52:53], v[36:37], v[2:3]
	s_waitcnt lgkmcnt(1)
	v_pk_fma_f32 v[0:1], v[54:55], v[46:47], v[0:1]
	v_lshlrev_b32_e32 v44, 16, v87
	v_and_b32_e32 v45, 0xffff0000, v87
	v_pk_fma_f32 v[2:3], v[56:57], v[40:41], v[2:3]
	v_lshlrev_b32_e32 v32, 16, v86
	v_and_b32_e32 v33, 0xffff0000, v86
	s_waitcnt lgkmcnt(0)
	v_pk_fma_f32 v[0:1], v[58:59], v[44:45], v[0:1]
	v_pk_fma_f32 v[36:37], v[60:61], v[32:33], v[2:3]
	v_mul_f32_e32 v44, 0xbfb8aa3b, v0
	v_mul_f32_e32 v45, 0xbfb8aa3b, v1
	v_mul_f32_e32 v2, 0xbfb8aa3b, v36
	v_exp_f32_e32 v44, v44
	v_exp_f32_e32 v45, v45
	v_exp_f32_e32 v2, v2
	v_mul_f32_e32 v3, 0xbfb8aa3b, v37
	v_exp_f32_e32 v3, v3
	v_add_f32_e32 v44, 1.0, v44
	v_add_f32_e32 v45, 1.0, v45
	v_add_f32_e32 v2, 1.0, v2
	v_rcp_f32_e32 v44, v44
	v_rcp_f32_e32 v45, v45
	v_rcp_f32_e32 v40, v2
	v_add_f32_e32 v2, 1.0, v3
	v_rcp_f32_e32 v97, v97
	v_rcp_f32_e32 v41, v2
	v_pk_mul_f32 v[0:1], v[0:1], v[44:45]
	v_pk_mul_f32 v[14:15], v[14:15], s[36:37] op_sel_hi:[1,0]
	v_pk_mul_f32 v[38:39], v[94:95], v[96:97]
	v_pk_mul_f32 v[4:5], v[4:5], s[36:37] op_sel_hi:[1,0]
	v_pk_mul_f32 v[6:7], v[6:7], v[62:63]
	v_pk_mul_f32 v[2:3], v[0:1], s[36:37] op_sel_hi:[1,0]
	v_pk_mul_f32 v[0:1], v[36:37], v[40:41]
	v_pk_mul_f32 v[34:35], v[34:35], s[36:37] op_sel_hi:[1,0]
	v_pk_mul_f32 v[42:43], v[92:93], s[36:37] op_sel_hi:[1,0]
	v_pk_mul_f32 v[38:39], v[38:39], s[36:37] op_sel_hi:[1,0]
	v_pk_mul_f32 v[32:33], v[6:7], s[36:37] op_sel_hi:[1,0]
	v_cvt_pk_bf16_f32 v44, v26, v27
	v_cvt_pk_bf16_f32 v45, v24, v25
	v_cvt_pk_bf16_f32 v46, v22, v23
	v_cvt_pk_bf16_f32 v47, v20, v21
	ds_write_b128 v85, v[44:47] offset:17408
	v_cvt_pk_bf16_f32 v44, v18, v19
	v_cvt_pk_bf16_f32 v45, v16, v17
	v_cvt_pk_bf16_f32 v46, v12, v13
	v_cvt_pk_bf16_f32 v47, v10, v11
	v_lshlrev_b32_e32 v6, 4, v79
	v_pk_mul_f32 v[0:1], v[0:1], s[36:37] op_sel_hi:[1,0]
	ds_write_b128 v85, v[44:47] offset:17424
	v_cvt_pk_bf16_f32 v44, v14, v15
	v_cvt_pk_bf16_f32 v45, v34, v35
	v_cvt_pk_bf16_f32 v46, v42, v43
	v_cvt_pk_bf16_f32 v47, v38, v39
	v_and_b32_e32 v57, 0x180, v6
	v_mul_f32_e32 v6, v83, v26
	ds_write_b128 v85, v[44:47] offset:17440
	v_cvt_pk_bf16_f32 v44, v4, v5
	v_cvt_pk_bf16_f32 v45, v32, v33
	v_cvt_pk_bf16_f32 v46, v2, v3
	v_cvt_pk_bf16_f32 v47, v0, v1
	v_lshrrev_b32_e32 v56, 5, v79
	v_cvt_pk_bf16_f32 v26, v6, s0
	v_lshlrev_b32_e32 v6, 11, v81
	ds_write_b128 v85, v[44:47] offset:17456
	v_bfe_u32 v85, v30, 2, 3
	v_lshl_add_u32 v6, v56, 9, v6
	v_or_b32_e32 v58, v6, v85
	v_or_b32_e32 v6, v58, v57
	v_ashrrev_i32_e32 v7, 31, v6
	v_lshlrev_b64 v[6:7], 1, v[6:7]
	v_lshl_add_u64 v[36:37], s[66:67], 0, v[6:7]
	global_store_short v[36:37], v26, off
	v_lshlrev_b32_e32 v26, 16, v26
	s_nop 1
	v_add_f32_dpp v200, v26, v26 row_ror:8 row_mask:0xf bank_mask:0xf
	s_nop 1
	v_add_f32_dpp v200, v200, v200 row_ror:4 row_mask:0xf bank_mask:0xf
	v_mul_f32_e32 v26, v83, v27
	v_or_b32_e32 v59, 8, v57
	v_cvt_pk_bf16_f32 v40, v26, s0
	v_or_b32_e32 v26, v58, v59
	v_ashrrev_i32_e32 v27, 31, v26
	v_lshlrev_b64 v[26:27], 1, v[26:27]
	v_lshl_add_u64 v[36:37], s[66:67], 0, v[26:27]
	global_store_short v[36:37], v40, off
	v_lshlrev_b32_e32 v36, 16, v40
	v_or_b32_e32 v60, 16, v57
	s_nop 1
	v_add_f32_dpp v201, v36, v36 row_ror:8 row_mask:0xf bank_mask:0xf
	s_nop 1
	v_add_f32_dpp v201, v201, v201 row_ror:4 row_mask:0xf bank_mask:0xf
	v_or_b32_e32 v36, v58, v60
	v_ashrrev_i32_e32 v37, 31, v36
	v_mul_f32_e32 v24, v83, v24
	v_lshlrev_b64 v[36:37], 1, v[36:37]
	v_cvt_pk_bf16_f32 v24, v24, s0
	v_lshl_add_u64 v[40:41], s[66:67], 0, v[36:37]
	global_store_short v[40:41], v24, off
	v_lshlrev_b32_e32 v24, 16, v24
	s_nop 1
	v_add_f32_dpp v202, v24, v24 row_ror:8 row_mask:0xf bank_mask:0xf
	s_nop 1
	v_add_f32_dpp v202, v202, v202 row_ror:4 row_mask:0xf bank_mask:0xf
	v_mul_f32_e32 v24, v83, v25
	v_or_b32_e32 v61, 24, v57
	v_cvt_pk_bf16_f32 v44, v24, s0
	v_or_b32_e32 v24, v58, v61
	v_ashrrev_i32_e32 v25, 31, v24
	v_lshlrev_b64 v[24:25], 1, v[24:25]
	v_lshl_add_u64 v[40:41], s[66:67], 0, v[24:25]
	global_store_short v[40:41], v44, off
	v_lshlrev_b32_e32 v40, 16, v44
	v_or_b32_e32 v62, 32, v57
	s_nop 1
	v_add_f32_dpp v203, v40, v40 row_ror:8 row_mask:0xf bank_mask:0xf
	s_nop 1
	v_add_f32_dpp v203, v203, v203 row_ror:4 row_mask:0xf bank_mask:0xf
	v_or_b32_e32 v40, v58, v62
	v_ashrrev_i32_e32 v41, 31, v40
	v_mul_f32_e32 v22, v83, v22
	v_lshlrev_b64 v[40:41], 1, v[40:41]
	v_cvt_pk_bf16_f32 v22, v22, s0
	v_lshl_add_u64 v[44:45], s[66:67], 0, v[40:41]
	global_store_short v[44:45], v22, off
	v_lshlrev_b32_e32 v22, 16, v22
	s_nop 1
	v_add_f32_dpp v204, v22, v22 row_ror:8 row_mask:0xf bank_mask:0xf
; DI bf16_t f2bf(float f) { return (bf16_t)(pk2(f, 0.f) & 0xffffu); }
; DI float bf2f(bf16_t h) { return __uint_as_float(((unsigned)h) << 16); }
; DI int fragoff(int row, int k, int KS) { return (((row >> 4) * KS + (k >> 5)) << 9) + (((((k >> 3) & 3) << 4) + (row & 15)) << 3) + (k & 7); }
; DI void mlstm_pre(const Params& p, int ch, char* smem) {
;     ...
;     for (int i = 0; i < 32; ++i) {
;       bf16_t kb = f2bf(a[i] * wgt);
;       o_kwT[fragoff(part * 32 + i, t, 2)] = kb;
;       atomicAdd(&s_kw[part * 32 + i], bf2f(kb));
	s_nop 1
	v_add_f32_dpp v204, v204, v204 row_ror:4 row_mask:0xf bank_mask:0xf
	v_mul_f32_e32 v22, v83, v23
	v_or_b32_e32 v63, 40, v57
	v_cvt_pk_bf16_f32 v46, v22, s0
	v_or_b32_e32 v22, v58, v63
	v_ashrrev_i32_e32 v23, 31, v22
	v_lshlrev_b64 v[22:23], 1, v[22:23]
	v_lshl_add_u64 v[44:45], s[66:67], 0, v[22:23]
	global_store_short v[44:45], v46, off
	v_lshlrev_b32_e32 v44, 16, v46
	v_or_b32_e32 v64, 48, v57
	s_nop 1
	v_add_f32_dpp v205, v44, v44 row_ror:8 row_mask:0xf bank_mask:0xf
	s_nop 1
	v_add_f32_dpp v205, v205, v205 row_ror:4 row_mask:0xf bank_mask:0xf
	v_or_b32_e32 v44, v58, v64
	v_ashrrev_i32_e32 v45, 31, v44
	v_mul_f32_e32 v20, v83, v20
	v_lshlrev_b64 v[44:45], 1, v[44:45]
	v_cvt_pk_bf16_f32 v20, v20, s0
	v_lshl_add_u64 v[46:47], s[66:67], 0, v[44:45]
	global_store_short v[46:47], v20, off
	v_lshlrev_b32_e32 v20, 16, v20
	s_nop 1
	v_add_f32_dpp v206, v20, v20 row_ror:8 row_mask:0xf bank_mask:0xf
	s_nop 1
	v_add_f32_dpp v206, v206, v206 row_ror:4 row_mask:0xf bank_mask:0xf
	v_mul_f32_e32 v20, v83, v21
	v_or_b32_e32 v65, 56, v57
	v_cvt_pk_bf16_f32 v48, v20, s0
	v_or_b32_e32 v20, v58, v65
	v_ashrrev_i32_e32 v21, 31, v20
	v_lshlrev_b64 v[20:21], 1, v[20:21]
	v_lshl_add_u64 v[46:47], s[66:67], 0, v[20:21]
	global_store_short v[46:47], v48, off
	v_lshlrev_b32_e32 v46, 16, v48
	v_or_b32_e32 v86, 64, v57
	s_nop 1
	v_add_f32_dpp v207, v46, v46 row_ror:8 row_mask:0xf bank_mask:0xf
	s_nop 1
	v_add_f32_dpp v207, v207, v207 row_ror:4 row_mask:0xf bank_mask:0xf
	v_or_b32_e32 v46, v58, v86
	v_ashrrev_i32_e32 v47, 31, v46
	v_mul_f32_e32 v18, v83, v18
	v_lshlrev_b64 v[46:47], 1, v[46:47]
	v_cvt_pk_bf16_f32 v18, v18, s0
	v_lshl_add_u64 v[48:49], s[66:67], 0, v[46:47]
	global_store_short v[48:49], v18, off
	v_lshlrev_b32_e32 v18, 16, v18
	s_nop 1
	v_add_f32_dpp v208, v18, v18 row_ror:8 row_mask:0xf bank_mask:0xf
	s_nop 1
	v_add_f32_dpp v208, v208, v208 row_ror:4 row_mask:0xf bank_mask:0xf
	v_mul_f32_e32 v18, v83, v19
	v_or_b32_e32 v87, 0x48, v57
	v_cvt_pk_bf16_f32 v50, v18, s0
	v_or_b32_e32 v18, v58, v87
	v_ashrrev_i32_e32 v19, 31, v18
	v_lshlrev_b64 v[18:19], 1, v[18:19]
	v_lshl_add_u64 v[48:49], s[66:67], 0, v[18:19]
	global_store_short v[48:49], v50, off
	v_lshlrev_b32_e32 v48, 16, v50
	v_or_b32_e32 v88, 0x50, v57
	s_nop 1
	v_add_f32_dpp v209, v48, v48 row_ror:8 row_mask:0xf bank_mask:0xf
	s_nop 1
	v_add_f32_dpp v209, v209, v209 row_ror:4 row_mask:0xf bank_mask:0xf
	v_or_b32_e32 v48, v58, v88
	v_ashrrev_i32_e32 v49, 31, v48
	v_mul_f32_e32 v16, v83, v16
	v_lshlrev_b64 v[48:49], 1, v[48:49]
	v_cvt_pk_bf16_f32 v16, v16, s0
	v_lshl_add_u64 v[50:51], s[66:67], 0, v[48:49]
	global_store_short v[50:51], v16, off
	v_lshlrev_b32_e32 v16, 16, v16
	s_nop 1
	v_add_f32_dpp v210, v16, v16 row_ror:8 row_mask:0xf bank_mask:0xf
	s_nop 1
	v_add_f32_dpp v210, v210, v210 row_ror:4 row_mask:0xf bank_mask:0xf
	v_mul_f32_e32 v16, v83, v17
	v_or_b32_e32 v89, 0x58, v57
	v_cvt_pk_bf16_f32 v52, v16, s0
	v_or_b32_e32 v16, v58, v89
	v_ashrrev_i32_e32 v17, 31, v16
	v_lshlrev_b64 v[16:17], 1, v[16:17]
	v_lshl_add_u64 v[50:51], s[66:67], 0, v[16:17]
	global_store_short v[50:51], v52, off
	v_lshlrev_b32_e32 v50, 16, v52
	v_or_b32_e32 v90, 0x60, v57
	s_nop 1
	v_add_f32_dpp v211, v50, v50 row_ror:8 row_mask:0xf bank_mask:0xf
	s_nop 1
	v_add_f32_dpp v211, v211, v211 row_ror:4 row_mask:0xf bank_mask:0xf
	v_or_b32_e32 v50, v58, v90
	v_ashrrev_i32_e32 v51, 31, v50
	v_mul_f32_e32 v12, v83, v12
	v_lshlrev_b64 v[50:51], 1, v[50:51]
	v_cvt_pk_bf16_f32 v12, v12, s0
	v_lshl_add_u64 v[52:53], s[66:67], 0, v[50:51]
	global_store_short v[52:53], v12, off
	v_lshlrev_b32_e32 v12, 16, v12
	s_nop 1
	v_add_f32_dpp v212, v12, v12 row_ror:8 row_mask:0xf bank_mask:0xf
	s_nop 1
	v_add_f32_dpp v212, v212, v212 row_ror:4 row_mask:0xf bank_mask:0xf
	v_mul_f32_e32 v12, v83, v13
	v_or_b32_e32 v91, 0x68, v57
	v_cvt_pk_bf16_f32 v54, v12, s0
	v_or_b32_e32 v12, v58, v91
	v_ashrrev_i32_e32 v13, 31, v12
	v_lshlrev_b64 v[12:13], 1, v[12:13]
	v_lshl_add_u64 v[52:53], s[66:67], 0, v[12:13]
	global_store_short v[52:53], v54, off
	v_lshlrev_b32_e32 v52, 16, v54
	v_or_b32_e32 v92, 0x70, v57
	s_nop 1
	v_add_f32_dpp v213, v52, v52 row_ror:8 row_mask:0xf bank_mask:0xf
	s_nop 1
	v_add_f32_dpp v213, v213, v213 row_ror:4 row_mask:0xf bank_mask:0xf
	v_or_b32_e32 v52, v58, v92
	v_ashrrev_i32_e32 v53, 31, v52
	v_mul_f32_e32 v10, v83, v10
	v_lshlrev_b64 v[52:53], 1, v[52:53]
	v_cvt_pk_bf16_f32 v10, v10, s0
	v_lshl_add_u64 v[54:55], s[66:67], 0, v[52:53]
	global_store_short v[54:55], v10, off
	v_lshlrev_b32_e32 v10, 16, v10
	s_nop 1
	v_add_f32_dpp v214, v10, v10 row_ror:8 row_mask:0xf bank_mask:0xf
	s_nop 1
	v_add_f32_dpp v214, v214, v214 row_ror:4 row_mask:0xf bank_mask:0xf
	v_mul_f32_e32 v10, v83, v11
	v_or_b32_e32 v94, 0x78, v57
	v_cvt_pk_bf16_f32 v93, v10, s0
	v_or_b32_e32 v10, v58, v94
	v_ashrrev_i32_e32 v11, 31, v10
	v_lshlrev_b64 v[10:11], 1, v[10:11]
	v_lshl_add_u64 v[54:55], s[66:67], 0, v[10:11]
	global_store_short v[54:55], v93, off
	v_lshlrev_b32_e32 v54, 16, v93
	s_nop 1
	v_add_f32_dpp v215, v54, v54 row_ror:8 row_mask:0xf bank_mask:0xf
	s_nop 1
	v_add_f32_dpp v215, v215, v215 row_ror:4 row_mask:0xf bank_mask:0xf
	v_lshl_add_u32 v54, v81, 2, v56
	v_lshl_add_u32 v81, v54, 9, v78
	v_or3_b32 v54, v57, v85, v81
	v_ashrrev_i32_e32 v55, 31, v54
	v_mul_f32_e32 v14, v83, v14
	v_lshlrev_b64 v[54:55], 1, v[54:55]
	v_cvt_pk_bf16_f32 v14, v14, s0
	v_lshl_add_u64 v[56:57], s[66:67], 0, v[54:55]
	global_store_short v[56:57], v14, off
	v_lshlrev_b32_e32 v14, 16, v14
	s_nop 1
	v_add_f32_dpp v216, v14, v14 row_ror:8 row_mask:0xf bank_mask:0xf
	s_nop 1
	v_add_f32_dpp v216, v216, v216 row_ror:4 row_mask:0xf bank_mask:0xf
; DI bf16_t f2bf(float f) { return (bf16_t)(pk2(f, 0.f) & 0xffffu); }
; DI float bf2f(bf16_t h) { return __uint_as_float(((unsigned)h) << 16); }
; DI int fragoff(int row, int k, int KS) { return (((row >> 4) * KS + (k >> 5)) << 9) + (((((k >> 3) & 3) << 4) + (row & 15)) << 3) + (k & 7); }
; DI void mlstm_pre(const Params& p, int ch, char* smem) {
;     ...
;     for (int i = 0; i < 32; ++i) {
;       bf16_t kb = f2bf(a[i] * wgt);
;       o_kwT[fragoff(part * 32 + i, t, 2)] = kb;
;       atomicAdd(&s_kw[part * 32 + i], bf2f(kb));
	v_mul_f32_e32 v14, v83, v15
	v_cvt_pk_bf16_f32 v58, v14, s0
	v_or3_b32 v14, v59, v85, v81
	v_ashrrev_i32_e32 v15, 31, v14
	v_lshlrev_b64 v[14:15], 1, v[14:15]
	v_lshl_add_u64 v[56:57], s[66:67], 0, v[14:15]
	global_store_short v[56:57], v58, off
	v_lshlrev_b32_e32 v56, 16, v58
	s_nop 1
	v_add_f32_dpp v217, v56, v56 row_ror:8 row_mask:0xf bank_mask:0xf
	s_nop 1
	v_add_f32_dpp v217, v217, v217 row_ror:4 row_mask:0xf bank_mask:0xf
	v_or3_b32 v56, v60, v85, v81
	v_ashrrev_i32_e32 v57, 31, v56
	v_mul_f32_e32 v34, v83, v34
	v_lshlrev_b64 v[56:57], 1, v[56:57]
	v_cvt_pk_bf16_f32 v34, v34, s0
	v_lshl_add_u64 v[58:59], s[66:67], 0, v[56:57]
	global_store_short v[58:59], v34, off
	v_lshlrev_b32_e32 v34, 16, v34
	s_nop 1
	v_add_f32_dpp v218, v34, v34 row_ror:8 row_mask:0xf bank_mask:0xf
	s_nop 1
	v_add_f32_dpp v218, v218, v218 row_ror:4 row_mask:0xf bank_mask:0xf
	v_mul_f32_e32 v34, v83, v35
	v_cvt_pk_bf16_f32 v60, v34, s0
	v_or3_b32 v34, v61, v85, v81
	v_ashrrev_i32_e32 v35, 31, v34
	v_lshlrev_b64 v[34:35], 1, v[34:35]
	v_lshl_add_u64 v[58:59], s[66:67], 0, v[34:35]
	global_store_short v[58:59], v60, off
	v_lshlrev_b32_e32 v58, 16, v60
	s_nop 1
	v_add_f32_dpp v219, v58, v58 row_ror:8 row_mask:0xf bank_mask:0xf
	s_nop 1
	v_add_f32_dpp v219, v219, v219 row_ror:4 row_mask:0xf bank_mask:0xf
	v_or3_b32 v58, v62, v85, v81
	v_ashrrev_i32_e32 v59, 31, v58
	v_mul_f32_e32 v42, v83, v42
	v_lshlrev_b64 v[58:59], 1, v[58:59]
	v_cvt_pk_bf16_f32 v42, v42, s0
	v_lshl_add_u64 v[60:61], s[66:67], 0, v[58:59]
	global_store_short v[60:61], v42, off
	v_lshlrev_b32_e32 v42, 16, v42
	s_nop 1
	v_add_f32_dpp v220, v42, v42 row_ror:8 row_mask:0xf bank_mask:0xf
	s_nop 1
	v_add_f32_dpp v220, v220, v220 row_ror:4 row_mask:0xf bank_mask:0xf
	v_mul_f32_e32 v42, v83, v43
	v_cvt_pk_bf16_f32 v62, v42, s0
	v_or3_b32 v42, v63, v85, v81
	v_ashrrev_i32_e32 v43, 31, v42
	v_lshlrev_b64 v[42:43], 1, v[42:43]
	v_lshl_add_u64 v[60:61], s[66:67], 0, v[42:43]
	global_store_short v[60:61], v62, off
	v_lshlrev_b32_e32 v60, 16, v62
	s_nop 1
	v_add_f32_dpp v221, v60, v60 row_ror:8 row_mask:0xf bank_mask:0xf
	s_nop 1
	v_add_f32_dpp v221, v221, v221 row_ror:4 row_mask:0xf bank_mask:0xf
	v_or3_b32 v60, v64, v85, v81
	v_ashrrev_i32_e32 v61, 31, v60
	v_mul_f32_e32 v38, v83, v38
	v_lshlrev_b64 v[60:61], 1, v[60:61]
	v_cvt_pk_bf16_f32 v38, v38, s0
	v_lshl_add_u64 v[62:63], s[66:67], 0, v[60:61]
	global_store_short v[62:63], v38, off
	v_lshlrev_b32_e32 v38, 16, v38
	s_nop 1
	v_add_f32_dpp v222, v38, v38 row_ror:8 row_mask:0xf bank_mask:0xf
	s_nop 1
	v_add_f32_dpp v222, v222, v222 row_ror:4 row_mask:0xf bank_mask:0xf
	v_mul_f32_e32 v38, v83, v39
	v_cvt_pk_bf16_f32 v64, v38, s0
	v_or3_b32 v38, v65, v85, v81
	v_ashrrev_i32_e32 v39, 31, v38
	v_lshlrev_b64 v[38:39], 1, v[38:39]
	v_lshl_add_u64 v[62:63], s[66:67], 0, v[38:39]
	global_store_short v[62:63], v64, off
	v_lshlrev_b32_e32 v62, 16, v64
	s_nop 1
	v_add_f32_dpp v223, v62, v62 row_ror:8 row_mask:0xf bank_mask:0xf
	s_nop 1
	v_add_f32_dpp v223, v223, v223 row_ror:4 row_mask:0xf bank_mask:0xf
	v_or3_b32 v62, v86, v85, v81
	v_ashrrev_i32_e32 v63, 31, v62
	v_mul_f32_e32 v4, v83, v4
	v_lshlrev_b64 v[62:63], 1, v[62:63]
	v_cvt_pk_bf16_f32 v4, v4, s0
	v_lshl_add_u64 v[64:65], s[66:67], 0, v[62:63]
	global_store_short v[64:65], v4, off
	v_lshlrev_b32_e32 v4, 16, v4
	s_nop 1
	v_add_f32_dpp v224, v4, v4 row_ror:8 row_mask:0xf bank_mask:0xf
	s_nop 1
	v_add_f32_dpp v224, v224, v224 row_ror:4 row_mask:0xf bank_mask:0xf
	v_mul_f32_e32 v4, v83, v5
	v_cvt_pk_bf16_f32 v86, v4, s0
	v_or3_b32 v4, v87, v85, v81
	v_ashrrev_i32_e32 v5, 31, v4
	v_lshlrev_b64 v[4:5], 1, v[4:5]
	v_lshl_add_u64 v[64:65], s[66:67], 0, v[4:5]
	global_store_short v[64:65], v86, off
	v_lshlrev_b32_e32 v64, 16, v86
	s_nop 1
	v_add_f32_dpp v225, v64, v64 row_ror:8 row_mask:0xf bank_mask:0xf
	s_nop 1
	v_add_f32_dpp v225, v225, v225 row_ror:4 row_mask:0xf bank_mask:0xf
	v_or3_b32 v64, v88, v85, v81
	v_ashrrev_i32_e32 v65, 31, v64
	v_mul_f32_e32 v32, v83, v32
	v_lshlrev_b64 v[64:65], 1, v[64:65]
	v_cvt_pk_bf16_f32 v32, v32, s0
	v_lshl_add_u64 v[86:87], s[66:67], 0, v[64:65]
	global_store_short v[86:87], v32, off
	v_lshlrev_b32_e32 v32, 16, v32
	s_nop 1
	v_add_f32_dpp v226, v32, v32 row_ror:8 row_mask:0xf bank_mask:0xf
	s_nop 1
	v_add_f32_dpp v226, v226, v226 row_ror:4 row_mask:0xf bank_mask:0xf
	v_mul_f32_e32 v32, v83, v33
	v_cvt_pk_bf16_f32 v88, v32, s0
	v_or3_b32 v32, v89, v85, v81
	v_ashrrev_i32_e32 v33, 31, v32
	v_lshlrev_b64 v[32:33], 1, v[32:33]
	v_lshl_add_u64 v[86:87], s[66:67], 0, v[32:33]
	global_store_short v[86:87], v88, off
	v_lshlrev_b32_e32 v86, 16, v88
	s_nop 1
	v_add_f32_dpp v227, v86, v86 row_ror:8 row_mask:0xf bank_mask:0xf
	s_nop 1
	v_add_f32_dpp v227, v227, v227 row_ror:4 row_mask:0xf bank_mask:0xf
	v_or3_b32 v86, v90, v85, v81
	v_ashrrev_i32_e32 v87, 31, v86
	v_mul_f32_e32 v2, v83, v2
	v_lshlrev_b64 v[86:87], 1, v[86:87]
	v_cvt_pk_bf16_f32 v2, v2, s0
	v_lshl_add_u64 v[88:89], s[66:67], 0, v[86:87]
	global_store_short v[88:89], v2, off
	v_lshlrev_b32_e32 v2, 16, v2
	s_nop 1
	v_add_f32_dpp v228, v2, v2 row_ror:8 row_mask:0xf bank_mask:0xf
	s_nop 1
	v_add_f32_dpp v228, v228, v228 row_ror:4 row_mask:0xf bank_mask:0xf
	v_mul_f32_e32 v2, v83, v3
	v_cvt_pk_bf16_f32 v90, v2, s0
	v_or3_b32 v2, v91, v85, v81
	v_ashrrev_i32_e32 v3, 31, v2
	v_lshlrev_b64 v[88:89], 1, v[2:3]
	v_lshl_add_u64 v[2:3], s[66:67], 0, v[88:89]
	global_store_short v[2:3], v90, off
	v_lshlrev_b32_e32 v2, 16, v90
	s_nop 1
	v_add_f32_dpp v229, v2, v2 row_ror:8 row_mask:0xf bank_mask:0xf
	s_nop 1
	v_add_f32_dpp v229, v229, v229 row_ror:4 row_mask:0xf bank_mask:0xf
	v_or3_b32 v2, v92, v85, v81
	v_ashrrev_i32_e32 v3, 31, v2
; DI bf16_t f2bf(float f) { return (bf16_t)(pk2(f, 0.f) & 0xffffu); }
; DI float bf2f(bf16_t h) { return __uint_as_float(((unsigned)h) << 16); }
; DI int fragoff(int row, int k, int KS) { return (((row >> 4) * KS + (k >> 5)) << 9) + (((((k >> 3) & 3) << 4) + (row & 15)) << 3) + (k & 7); }
; DI void mlstm_pre(const Params& p, int ch, char* smem) {
;     ...
;     for (int i = 0; i < 32; ++i) {
;       bf16_t kb = f2bf(a[i] * wgt);
;       o_kwT[fragoff(part * 32 + i, t, 2)] = kb;
;       atomicAdd(&s_kw[part * 32 + i], bf2f(kb));
;     }
;     const uint4* vsrc = (const uint4*)(P + (size_t)(tok0 + t) * 4096 + 3072 + h * 128 + part * 32);
; #pragma unroll
;     for (int q = 0; q < 4; ++q) {
;       uint4 v = vsrc[q];
;       const unsigned uu[4] = {v.x, v.y, v.z, v.w};
; #pragma unroll
;       for (int e = 0; e < 4; ++e) {
;         o_vT[fragoff(part * 32 + 8 * q + 2 * e, t, 2)] = (bf16_t)(uu[e] & 0xffffu);
;         o_vT[fragoff(part * 32 + 8 * q + 2 * e + 1, t, 2)] = (bf16_t)(uu[e] >> 16);
;       }
;     }
	v_mul_f32_e32 v0, v83, v0
	v_lshlrev_b64 v[90:91], 1, v[2:3]
	v_cvt_pk_bf16_f32 v0, v0, s0
	v_lshl_add_u64 v[2:3], s[66:67], 0, v[90:91]
	global_store_short v[2:3], v0, off
	v_lshlrev_b32_e32 v0, 16, v0
	s_nop 1
	v_add_f32_dpp v232, v0, v0 row_ror:8 row_mask:0xf bank_mask:0xf
	s_nop 1
	v_add_f32_dpp v232, v232, v232 row_ror:4 row_mask:0xf bank_mask:0xf
	v_mul_f32_e32 v0, v83, v1
	v_cvt_pk_bf16_f32 v2, v0, s0
	v_or3_b32 v0, v94, v85, v81
	v_ashrrev_i32_e32 v1, 31, v0
	v_lshlrev_b64 v[92:93], 1, v[0:1]
	v_lshl_add_u64 v[0:1], s[66:67], 0, v[92:93]
	global_store_short v[0:1], v2, off
	v_lshlrev_b32_e32 v0, 16, v2
	s_nop 1
	v_add_f32_dpp v233, v0, v0 row_ror:8 row_mask:0xf bank_mask:0xf
	s_nop 1
	v_add_f32_dpp v233, v233, v233 row_ror:4 row_mask:0xf bank_mask:0xf
	v_lshrrev_b32_e32 v234, 4, v192
	v_and_b32_e32 v235, 3, v192
	v_lshl_add_u32 v234, v234, 2, v235
	v_mul_u32_u24_e32 v234, 0x84, v234
	v_add_u32_e32 v234, 0xb000, v234
	s_mov_b64 s[100:101], exec
	s_mov_b32 s98, 0xf000f
	s_mov_b32 s99, 0xf000f
	s_and_b64 exec, s[98:99], s[100:101]
	ds_write_b32 v234, v200 offset:0
	ds_write_b32 v234, v201 offset:4
	ds_write_b32 v234, v202 offset:8
	ds_write_b32 v234, v203 offset:12
	ds_write_b32 v234, v204 offset:16
	ds_write_b32 v234, v205 offset:20
	ds_write_b32 v234, v206 offset:24
	ds_write_b32 v234, v207 offset:28
	ds_write_b32 v234, v208 offset:32
	ds_write_b32 v234, v209 offset:36
	ds_write_b32 v234, v210 offset:40
	ds_write_b32 v234, v211 offset:44
	ds_write_b32 v234, v212 offset:48
	ds_write_b32 v234, v213 offset:52
	ds_write_b32 v234, v214 offset:56
	ds_write_b32 v234, v215 offset:60
	ds_write_b32 v234, v216 offset:64
	ds_write_b32 v234, v217 offset:68
	ds_write_b32 v234, v218 offset:72
	ds_write_b32 v234, v219 offset:76
	ds_write_b32 v234, v220 offset:80
	ds_write_b32 v234, v221 offset:84
	ds_write_b32 v234, v222 offset:88
	ds_write_b32 v234, v223 offset:92
	ds_write_b32 v234, v224 offset:96
	ds_write_b32 v234, v225 offset:100
	ds_write_b32 v234, v226 offset:104
	ds_write_b32 v234, v227 offset:108
	ds_write_b32 v234, v228 offset:112
	ds_write_b32 v234, v229 offset:116
	ds_write_b32 v234, v232 offset:120
	ds_write_b32 v234, v233 offset:124
	s_mov_b64 exec, s[100:101]
	v_lshl_add_u64 v[0:1], s[86:87], 0, v[8:9]
	v_lshl_add_u64 v[0:1], v[0:1], 0, s[34:35]
	v_lshl_add_u64 v[8:9], v[0:1], 0, v[28:29]
	s_movk_i32 s8, 0x1000
	v_add_co_u32_e64 v0, s[8:9], s8, v8
	v_lshl_add_u64 v[6:7], s[64:65], 0, v[6:7]
	s_nop 0
	v_addc_co_u32_e64 v1, s[8:9], 0, v9, s[8:9]
	global_load_dwordx4 v[0:3], v[0:1], off offset:2048
	v_lshl_add_u64 v[8:9], v[8:9], 0, s[42:43]
	v_lshl_add_u64 v[4:5], s[64:65], 0, v[4:5]
	s_waitcnt vmcnt(0)
	global_store_short v[6:7], v0, off
	v_lshl_add_u64 v[6:7], s[64:65], 0, v[26:27]
	global_store_short_d16_hi v[6:7], v0, off
	v_lshl_add_u64 v[6:7], s[64:65], 0, v[36:37]
	global_store_short v[6:7], v1, off
	v_lshl_add_u64 v[6:7], s[64:65], 0, v[24:25]
	global_store_short_d16_hi v[6:7], v1, off
	v_lshl_add_u64 v[0:1], s[64:65], 0, v[40:41]
	global_store_short v[0:1], v2, off
	v_lshl_add_u64 v[0:1], s[64:65], 0, v[22:23]
	global_store_short_d16_hi v[0:1], v2, off
	v_lshl_add_u64 v[0:1], s[64:65], 0, v[44:45]
	global_store_short v[0:1], v3, off
	v_lshl_add_u64 v[0:1], s[64:65], 0, v[20:21]
	global_store_short_d16_hi v[0:1], v3, off
	global_load_dwordx4 v[0:3], v[8:9], off offset:16
	v_lshl_add_u64 v[6:7], s[64:65], 0, v[46:47]
	v_and_b32_e32 v21, 31, v30
	s_waitcnt vmcnt(0)
	global_store_short v[6:7], v0, off
	v_lshl_add_u64 v[6:7], s[64:65], 0, v[18:19]
	global_store_short_d16_hi v[6:7], v0, off
	v_lshl_add_u64 v[6:7], s[64:65], 0, v[48:49]
	global_store_short v[6:7], v1, off
	v_lshl_add_u64 v[6:7], s[64:65], 0, v[16:17]
	global_store_short_d16_hi v[6:7], v1, off
	v_lshl_add_u64 v[0:1], s[64:65], 0, v[50:51]
	global_store_short v[0:1], v2, off
	v_lshl_add_u64 v[0:1], s[64:65], 0, v[12:13]
	global_store_short_d16_hi v[0:1], v2, off
	v_lshl_add_u64 v[0:1], s[64:65], 0, v[52:53]
	global_store_short v[0:1], v3, off
	v_lshl_add_u64 v[0:1], s[64:65], 0, v[10:11]
	global_store_short_d16_hi v[0:1], v3, off
	global_load_dwordx4 v[0:3], v[8:9], off offset:32
	v_lshl_add_u64 v[6:7], s[64:65], 0, v[54:55]
	v_bfe_u32 v16, v30, 6, 1
	v_lshl_or_b32 v17, v16, 5, v21
	s_waitcnt vmcnt(0)
	global_store_short v[6:7], v0, off
	v_lshl_add_u64 v[6:7], s[64:65], 0, v[14:15]
	global_store_short_d16_hi v[6:7], v0, off
	v_lshl_add_u64 v[6:7], s[64:65], 0, v[56:57]
	global_store_short v[6:7], v1, off
	v_lshl_add_u64 v[6:7], s[64:65], 0, v[34:35]
	global_store_short_d16_hi v[6:7], v1, off
	v_lshl_add_u64 v[0:1], s[64:65], 0, v[58:59]
	global_store_short v[0:1], v2, off
	v_lshl_add_u64 v[0:1], s[64:65], 0, v[42:43]
	global_store_short_d16_hi v[0:1], v2, off
	v_lshl_add_u64 v[0:1], s[64:65], 0, v[60:61]
	global_store_short v[0:1], v3, off
	v_lshl_add_u64 v[0:1], s[64:65], 0, v[38:39]
	global_store_short_d16_hi v[0:1], v3, off
	global_load_dwordx4 v[0:3], v[8:9], off offset:48
	v_lshl_add_u64 v[6:7], s[64:65], 0, v[62:63]
	s_waitcnt vmcnt(0)
	global_store_short_d16_hi v[4:5], v0, off
	v_lshl_add_u64 v[4:5], s[64:65], 0, v[64:65]
	global_store_short v[4:5], v1, off
	v_lshl_add_u64 v[4:5], s[64:65], 0, v[32:33]
	global_store_short v[6:7], v0, off
	global_store_short_d16_hi v[4:5], v1, off
	v_lshl_add_u64 v[0:1], s[64:65], 0, v[86:87]
	global_store_short v[0:1], v2, off
	v_lshl_add_u64 v[0:1], s[64:65], 0, v[88:89]
	global_store_short_d16_hi v[0:1], v2, off
	v_lshl_add_u64 v[0:1], s[64:65], 0, v[90:91]
	global_store_short v[0:1], v3, off
	v_lshl_add_u64 v[0:1], s[64:65], 0, v[92:93]
	global_store_short_d16_hi v[0:1], v3, off
	v_lshrrev_b32_e32 v1, 1, v30
	v_bfi_b32 v0, s79, v79, v30
	v_and_b32_e32 v4, 16, v1
	v_mad_u64_u32 v[18:19], s[8:9], v0, s75, v[4:5]
	s_waitcnt lgkmcnt(0)
	s_barrier
; #define MFMA32(a, b, c) __builtin_amdgcn_mfma_f32_32x32x16_bf16((a), (b), (c), 0, 0, 0)
; DI int crow32(int r, int half) { return (r & 3) + 8 * (r >> 2) + 4 * half; }
; DI void mlstm_pre(const Params& p, int ch, char* smem) {
;     ...
;   __syncthreads();
;   {
;     const int ti = wave >> 1, tj = wave & 1;
;     f32x16 acc;
; #pragma unroll
;     for (int r = 0; r < 16; ++r) acc[r] = 0.f;
; #pragma unroll
;     for (int s = 0; s < 8; ++s) {
;       const int ko = s * 16 + (lane >> 5) * 8;
;       bf16x8 bk = *(const bf16x8*)(ks + (tj * 32 + (lane & 31)) * 136 + ko);
;       bf16x8 aq = *(const bf16x8*)(qs + (ti * 32 + (lane & 31)) * 136 + ko);
;       acc = MFMA32(aq, bk, acc);
;     }
;     const int j = tj * 32 + (lane & 31);
;     const float cj = s_li[j] - s_bc[j];
; #pragma unroll
;     for (int r = 0; r < 16; ++r) {
;       const int i = ti * 32 + crow32(r, lane >> 5);
;       float pv = (i >= j) ? acc[r] * __expf(s_bc[i] + cj - s_mt[i]) : 0.f;
	ds_read_b128 v[0:3], v18
	v_mad_u32_u24 v19, v17, s75, v4
	ds_read_b128 v[4:7], v19 offset:17408
	ds_read_b128 v[22:25], v19 offset:17440
	ds_read_b128 v[32:35], v18 offset:32
	s_waitcnt lgkmcnt(2)
	v_mfma_f32_32x32x16_bf16 v[0:15], v[0:3], v[4:7], 0
	s_waitcnt lgkmcnt(0)
	v_mfma_f32_32x32x16_bf16 v[0:15], v[32:35], v[22:25], v[0:15]
	ds_read_b128 v[22:25], v18 offset:64
	ds_read_b128 v[32:35], v19 offset:17472
	ds_read_b128 v[36:39], v19 offset:17504
	ds_read_b128 v[40:43], v18 offset:96
	s_waitcnt lgkmcnt(2)
	v_mfma_f32_32x32x16_bf16 v[0:15], v[22:25], v[32:35], v[0:15]
	s_waitcnt lgkmcnt(0)
	v_mfma_f32_32x32x16_bf16 v[0:15], v[40:43], v[36:39], v[0:15]
	ds_read_b128 v[22:25], v18 offset:128
	ds_read_b128 v[32:35], v19 offset:17536
	ds_read_b128 v[36:39], v19 offset:17568
	ds_read_b128 v[40:43], v18 offset:160
	s_waitcnt lgkmcnt(2)
	v_mfma_f32_32x32x16_bf16 v[0:15], v[22:25], v[32:35], v[0:15]
	s_waitcnt lgkmcnt(0)
	v_mfma_f32_32x32x16_bf16 v[0:15], v[40:43], v[36:39], v[0:15]
	ds_read_b128 v[22:25], v18 offset:192
	ds_read_b128 v[32:35], v19 offset:17600
	ds_read_b128 v[36:39], v19 offset:17632
	ds_read_b128 v[40:43], v18 offset:224
	v_mul_i32_i24_e32 v18, 0xfffffef4, v17
	v_mad_u32_u24 v18, v17, s75, v18
	ds_read2st64_b32 v[18:19], v18 offset0:136 offset1:138
	s_waitcnt lgkmcnt(0)
	v_sub_f32_e32 v19, v18, v19
	v_mfma_f32_32x32x16_bf16 v[0:15], v[22:25], v[32:35], v[0:15]
	v_lshrrev_b32_e32 v18, 3, v30
	v_and_b32_e32 v22, 0xffffffe0, v79
	v_and_b32_e32 v23, 4, v18
	v_or_b32_e32 v20, v23, v22
	v_cmp_ge_i32_e64 s[8:9], v20, v17
	v_mov_b32_e32 v24, 0
	v_lshlrev_b32_e32 v18, 2, v20
	v_mfma_f32_32x32x16_bf16 v[0:15], v[40:43], v[36:39], v[0:15]
	s_and_saveexec_b64 s[10:11], s[8:9]
	s_cbranch_execz .LBB0_406
	ds_read2st64_b32 v[24:25], v18 offset0:138 offset1:140
	s_waitcnt lgkmcnt(0)
	v_add_f32_e32 v24, v19, v24
	v_sub_f32_e32 v24, v24, v25
	v_mul_f32_e32 v24, 0x3fb8aa3b, v24
	v_exp_f32_e32 v24, v24
	s_nop 3
	v_mul_f32_e32 v24, v0, v24

; DI void mlstm_pre(const Params& p, int ch, char* smem) {
;     ...
;   if (tid < 64) { ms[tid] = s_rs[tid]; ms[64 + tid] = fl_val; }
;   if (tid < 128) ms[256 + tid] = s_kw[tid];
.LBB0_470:
	s_or_b64 exec, exec, s[8:9]
	s_and_saveexec_b64 s[6:7], vcc
	s_cbranch_execz .LBB0_375
	v_lshrrev_b32_e32 v234, 5, v30
	v_and_b32_e32 v235, 31, v30
	v_mad_u32_u24 v234, v234, 33, v235
	v_lshlrev_b32_e32 v234, 2, v234
	v_add_u32_e32 v234, 0xb000, v234
	ds_read_b32 v236, v234 offset:0
	ds_read_b32 v237, v234 offset:528
	ds_read_b32 v238, v234 offset:1056
	ds_read_b32 v239, v234 offset:1584
	ds_read_b32 v240, v234 offset:2112
	ds_read_b32 v241, v234 offset:2640
	ds_read_b32 v242, v234 offset:3168
	ds_read_b32 v243, v234 offset:3696
	ds_read_b32 v244, v234 offset:4224
	ds_read_b32 v245, v234 offset:4752
	ds_read_b32 v246, v234 offset:5280
	ds_read_b32 v247, v234 offset:5808
	ds_read_b32 v248, v234 offset:6336
	ds_read_b32 v249, v234 offset:6864
	ds_read_b32 v250, v234 offset:7392
	ds_read_b32 v251, v234 offset:7920
	v_lshl_add_u64 v[0:1], v[30:31], 2, s[16:17]
	s_waitcnt lgkmcnt(0)
	v_add_f32_e32 v2, v236, v237
	v_add_f32_e32 v2, v2, v238
	v_add_f32_e32 v2, v2, v239
	v_add_f32_e32 v2, v2, v240
	v_add_f32_e32 v2, v2, v241
	v_add_f32_e32 v2, v2, v242
	v_add_f32_e32 v2, v2, v243
	v_add_f32_e32 v2, v2, v244
	v_add_f32_e32 v2, v2, v245
	v_add_f32_e32 v2, v2, v246
	v_add_f32_e32 v2, v2, v247
	v_add_f32_e32 v2, v2, v248
	v_add_f32_e32 v2, v2, v249
	v_add_f32_e32 v2, v2, v250
	v_add_f32_e32 v2, v2, v251
	global_store_dword v[0:1], v2, off offset:1024
	s_branch .LBB0_375
